# kv tasks: K-row loads hoisted into the first load round (one memory round trip instead of two)
# speedup vs baseline: 1.0027x; 1.0027x over previous
.LBB0_425:
	v_add_u32_e32 v48, s0, v35
	v_add_u32_e32 v49, s0, v34
	v_max_i32_e32 v41, 0, v48
	v_min_i32_e32 v42, s40, v49
	v_sub_u32_e32 v41, v42, v41
	v_cvt_f32_i32_e32 v41, v41
	v_add_u32_e32 v50, s69, v38
	v_add_u32_e32 v52, s69, v37
	v_add_u32_e32 v53, s69, v36
	v_div_scale_f32 v42, s[28:29], v41, v41, v40
	v_rcp_f32_e32 v43, v42
	s_add_i32 s0, s0, 8
	v_add_u32_e32 v51, s69, v39
	v_add_u32_e32 v36, 0x2000, v36
	v_fma_f32 v44, -v42, v43, 1.0
	v_fmac_f32_e32 v43, v44, v43
	v_div_scale_f32 v44, vcc, v40, v41, v40
	v_mul_f32_e32 v45, v44, v43
	v_fma_f32 v46, -v42, v45, v44
	v_fmac_f32_e32 v45, v46, v43
	v_fma_f32 v42, -v42, v45, v44
	v_div_fmas_f32 v42, v42, v43, v45
	v_div_fixup_f32 v41, v42, v41, v40
	ds_read2st64_b32 v[42:43], v50 offset1:4
	ds_read2st64_b32 v[44:45], v52 offset1:4
	ds_read2st64_b32 v[46:47], v53 offset1:4
	v_add_u32_e32 v37, 0x2000, v37
	v_add_u32_e32 v38, 0x2000, v38
	s_waitcnt lgkmcnt(2)
	v_sub_f32_e32 v41, v41, v42
	v_cvt_pk_bf16_f32 v41, v41, s0
	ds_write_b16 v51, v41
	s_waitcnt lgkmcnt(1)
	v_sub_f32_e32 v41, v44, v46
	v_add_f32_e32 v40, v40, v41
	v_add_u32_e32 v41, 1, v48
	v_add_u32_e32 v42, 1, v49
	v_max_i32_e32 v41, 0, v41
	v_min_i32_e32 v42, s40, v42
	v_sub_u32_e32 v41, v42, v41
	v_cvt_f32_i32_e32 v41, v41
	v_add_u32_e32 v39, 0x1080, v39
	s_cmp_lg_u32 s0, 32
	v_div_scale_f32 v42, s[28:29], v41, v41, v40
	v_rcp_f32_e32 v44, v42
	s_nop 0
	v_fma_f32 v46, -v42, v44, 1.0
	v_fmac_f32_e32 v44, v46, v44
	v_div_scale_f32 v46, vcc, v40, v41, v40
	v_mul_f32_e32 v54, v46, v44
	v_fma_f32 v55, -v42, v54, v46
	v_fmac_f32_e32 v54, v55, v44
	v_fma_f32 v42, -v42, v54, v46
	v_div_fmas_f32 v42, v42, v44, v54
	v_div_fixup_f32 v41, v42, v41, v40
	v_sub_f32_e32 v41, v41, v43
	v_cvt_pk_bf16_f32 v41, v41, s0
	ds_write_b16 v51, v41 offset:528
	v_sub_f32_e32 v41, v45, v47
	v_add_f32_e32 v46, v40, v41
	v_add_u32_e32 v40, 2, v48
	v_add_u32_e32 v41, 2, v49
	v_max_i32_e32 v40, 0, v40
	v_min_i32_e32 v41, s40, v41
	v_sub_u32_e32 v40, v41, v40
	v_cvt_f32_i32_e32 v40, v40
	v_div_scale_f32 v41, s[28:29], v40, v40, v46
	v_rcp_f32_e32 v42, v41
	s_nop 0
	v_fma_f32 v43, -v41, v42, 1.0
	v_fmac_f32_e32 v42, v43, v42
	v_div_scale_f32 v43, vcc, v46, v40, v46
	v_mul_f32_e32 v44, v43, v42
	v_fma_f32 v45, -v41, v44, v43
	v_fmac_f32_e32 v44, v45, v42
	v_fma_f32 v41, -v41, v44, v43
	v_div_fmas_f32 v41, v41, v42, v44
	v_div_fixup_f32 v42, v41, v40, v46
	ds_read2st64_b32 v[40:41], v50 offset0:8 offset1:12
	s_waitcnt lgkmcnt(0)
	v_sub_f32_e32 v40, v42, v40
	v_cvt_pk_bf16_f32 v40, v40, s0
	ds_write_b16 v51, v40 offset:1056
	ds_read2st64_b32 v[42:43], v52 offset0:8 offset1:12
	ds_read2st64_b32 v[44:45], v53 offset0:8 offset1:12
	s_waitcnt lgkmcnt(0)
	v_sub_f32_e32 v40, v42, v44
	v_add_u32_e32 v42, 3, v48
	v_add_u32_e32 v44, 3, v49
	v_max_i32_e32 v42, 0, v42
	v_min_i32_e32 v44, s40, v44
	v_sub_u32_e32 v42, v44, v42
	v_cvt_f32_i32_e32 v42, v42
	v_add_f32_e32 v40, v46, v40
	v_div_scale_f32 v44, s[28:29], v42, v42, v40
	v_rcp_f32_e32 v46, v44
	s_nop 0
	v_fma_f32 v47, -v44, v46, 1.0
	v_fmac_f32_e32 v46, v47, v46
	v_div_scale_f32 v47, vcc, v40, v42, v40
	v_mul_f32_e32 v54, v47, v46
	v_fma_f32 v55, -v44, v54, v47
	v_fmac_f32_e32 v54, v55, v46
	v_fma_f32 v44, -v44, v54, v47
	v_div_fmas_f32 v44, v44, v46, v54
	v_div_fixup_f32 v42, v44, v42, v40
	v_sub_f32_e32 v41, v42, v41
	v_cvt_pk_bf16_f32 v41, v41, s0
	ds_write_b16 v51, v41 offset:1584
	v_sub_f32_e32 v41, v43, v45
	v_add_f32_e32 v46, v40, v41
	v_add_u32_e32 v40, 4, v48
	v_add_u32_e32 v41, 4, v49
	v_max_i32_e32 v40, 0, v40
	v_min_i32_e32 v41, s40, v41
	v_sub_u32_e32 v40, v41, v40
	v_cvt_f32_i32_e32 v40, v40
	v_div_scale_f32 v41, s[28:29], v40, v40, v46
	v_rcp_f32_e32 v42, v41
	s_nop 0
	v_fma_f32 v43, -v41, v42, 1.0
	v_fmac_f32_e32 v42, v43, v42
	v_div_scale_f32 v43, vcc, v46, v40, v46
	v_mul_f32_e32 v44, v43, v42
	v_fma_f32 v45, -v41, v44, v43
	v_fmac_f32_e32 v44, v45, v42
	v_fma_f32 v41, -v41, v44, v43
	v_div_fmas_f32 v41, v41, v42, v44
	v_div_fixup_f32 v42, v41, v40, v46
	ds_read2st64_b32 v[40:41], v50 offset0:16 offset1:20
	s_waitcnt lgkmcnt(0)
	v_sub_f32_e32 v40, v42, v40
	v_cvt_pk_bf16_f32 v40, v40, s0
	ds_write_b16 v51, v40 offset:2112
	ds_read2st64_b32 v[42:43], v52 offset0:16 offset1:20
	ds_read2st64_b32 v[44:45], v53 offset0:16 offset1:20
	s_waitcnt lgkmcnt(0)
	v_sub_f32_e32 v40, v42, v44
	v_add_u32_e32 v42, 5, v48
	v_add_u32_e32 v44, 5, v49
	v_max_i32_e32 v42, 0, v42
	v_min_i32_e32 v44, s40, v44
	v_sub_u32_e32 v42, v44, v42
	v_cvt_f32_i32_e32 v42, v42
	v_add_f32_e32 v40, v46, v40
	v_div_scale_f32 v44, s[28:29], v42, v42, v40
	v_rcp_f32_e32 v46, v44
	s_nop 0
	v_fma_f32 v47, -v44, v46, 1.0
	v_fmac_f32_e32 v46, v47, v46
	v_div_scale_f32 v47, vcc, v40, v42, v40
	v_mul_f32_e32 v54, v47, v46
	v_fma_f32 v55, -v44, v54, v47
	v_fmac_f32_e32 v54, v55, v46
	v_fma_f32 v44, -v44, v54, v47
	v_div_fmas_f32 v44, v44, v46, v54
	v_div_fixup_f32 v42, v44, v42, v40
	v_sub_f32_e32 v41, v42, v41
	v_cvt_pk_bf16_f32 v41, v41, s0
	ds_write_b16 v51, v41 offset:2640
	v_sub_f32_e32 v41, v43, v45
	v_add_f32_e32 v46, v40, v41
	v_add_u32_e32 v40, 6, v48
	v_add_u32_e32 v41, 6, v49
	v_max_i32_e32 v40, 0, v40
	v_min_i32_e32 v41, s40, v41
	v_sub_u32_e32 v40, v41, v40
	v_cvt_f32_i32_e32 v40, v40
	v_div_scale_f32 v41, s[28:29], v40, v40, v46
	v_rcp_f32_e32 v42, v41
	s_nop 0
	v_fma_f32 v43, -v41, v42, 1.0
	v_fmac_f32_e32 v42, v43, v42
	v_div_scale_f32 v43, vcc, v46, v40, v46
	v_mul_f32_e32 v44, v43, v42
	v_fma_f32 v45, -v41, v44, v43
	v_fmac_f32_e32 v44, v45, v42
	v_fma_f32 v41, -v41, v44, v43
	v_div_fmas_f32 v41, v41, v42, v44
	v_div_fixup_f32 v42, v41, v40, v46
	ds_read2st64_b32 v[40:41], v50 offset0:24 offset1:28
	s_waitcnt lgkmcnt(0)
	v_sub_f32_e32 v40, v42, v40
	v_cvt_pk_bf16_f32 v40, v40, s0
	ds_write_b16 v51, v40 offset:3168
	ds_read2st64_b32 v[42:43], v52 offset0:24 offset1:28
	ds_read2st64_b32 v[44:45], v53 offset0:24 offset1:28
	s_waitcnt lgkmcnt(0)
	v_sub_f32_e32 v40, v42, v44
	v_add_u32_e32 v42, 7, v48
	v_add_u32_e32 v44, 7, v49
	v_max_i32_e32 v42, 0, v42
	v_min_i32_e32 v44, s40, v44
	v_sub_u32_e32 v42, v44, v42
	v_cvt_f32_i32_e32 v42, v42
	v_add_f32_e32 v40, v46, v40
	v_div_scale_f32 v44, s[28:29], v42, v42, v40
	v_rcp_f32_e32 v46, v44
	s_nop 0
	v_fma_f32 v47, -v44, v46, 1.0
	v_fmac_f32_e32 v46, v47, v46
	v_div_scale_f32 v47, vcc, v40, v42, v40
	v_mul_f32_e32 v48, v47, v46
	v_fma_f32 v49, -v44, v48, v47
	v_fmac_f32_e32 v48, v49, v46
	v_fma_f32 v44, -v44, v48, v47
	v_div_fmas_f32 v44, v44, v46, v48
	v_div_fixup_f32 v42, v44, v42, v40
	v_sub_f32_e32 v41, v42, v41
	v_cvt_pk_bf16_f32 v41, v41, s0
	ds_write_b16 v51, v41 offset:3696
	v_sub_f32_e32 v41, v43, v45
	v_add_f32_e32 v40, v40, v41
	s_cbranch_scc1 .LBB0_425
	v_and_b32_e32 v33, 0xffffff80, v33
	v_add_u32_e32 v33, s69, v33
	v_mul_u32_u24_e32 v34, 0x210, v87
	s_waitcnt lgkmcnt(0)
	s_barrier
	v_add3_u32 v33, v33, v200, v34
	ds_read_b128 v[34:37], v33 offset:49152
	ds_read_b128 v[38:41], v33 offset:49216
	ds_read_b128 v[54:57], v33 offset:57600
	ds_read_b128 v[58:61], v33 offset:57664
	s_waitcnt vmcnt(11) lgkmcnt(3)
	v_mfma_f32_16x16x32_bf16 v[42:45], v[34:37], v[20:23], 0
	v_lshl_or_b32 v64, v32, 2, s3
	v_and_b32_e32 v62, 0xffffffcf, v82
	v_ashrrev_i32_e32 v63, 31, v62
	s_waitcnt vmcnt(7) lgkmcnt(2)
	v_mfma_f32_16x16x32_bf16 v[42:45], v[38:41], v[4:7], v[42:45]
	v_lshlrev_b64 v[62:63], 1, v[62:63]
	v_ashrrev_i32_e32 v65, 31, v64
	s_addk_i32 s2, 0x100
	s_waitcnt lgkmcnt(1)
	v_mfma_f32_16x16x32_bf16 v[20:23], v[54:57], v[20:23], 0
	s_ashr_i32 s29, s2, 3
	s_waitcnt vmcnt(3)
	s_nop 0
	v_mul_f32_e32 v32, v86, v42
	v_cvt_pk_bf16_f32 v42, v32, s0
	v_mfma_f32_16x16x32_bf16 v[46:49], v[34:37], v[16:19], 0
	v_lshlrev_b64 v[32:33], 11, v[64:65]
	v_lshl_add_u64 v[66:67], s[22:23], 0, v[32:33]
	v_mul_f32_e32 v32, v86, v43
	v_mfma_f32_16x16x32_bf16 v[16:19], v[54:57], v[16:19], 0
	v_cvt_pk_bf16_f32 v65, v32, s0
	v_or_b32_e32 v32, 1, v64
	v_ashrrev_i32_e32 v33, 31, v32
	s_waitcnt lgkmcnt(0)
	v_mfma_f32_16x16x32_bf16 v[4:7], v[58:61], v[4:7], v[20:23]
	v_lshl_add_u64 v[68:69], v[66:67], 0, v[62:63]
	v_lshlrev_b64 v[32:33], 11, v[32:33]
	global_store_short v[68:69], v42, off offset:1024
	v_mul_f32_e32 v20, v86, v45
	v_cvt_pk_bf16_f32 v22, v20, s0
	v_or_b32_e32 v20, 3, v64
	v_ashrrev_i32_e32 v21, 31, v20
	v_mfma_f32_16x16x32_bf16 v[46:49], v[38:41], v[8:11], v[46:49]
	v_mul_f32_e32 v4, v86, v4
	v_cvt_pk_bf16_f32 v4, v4, s0
	v_lshl_add_u64 v[42:43], s[22:23], 0, v[32:33]
	v_mfma_f32_16x16x32_bf16 v[8:11], v[58:61], v[8:11], v[16:19]
	v_mul_f32_e32 v32, v86, v44
	v_cvt_pk_bf16_f32 v44, v32, s0
	v_or_b32_e32 v32, 2, v64
	v_lshlrev_b64 v[16:17], 11, v[20:21]
	v_or_b32_e32 v20, 16, v64
	v_ashrrev_i32_e32 v21, 31, v20
	v_mfma_f32_16x16x32_bf16 v[50:53], v[34:37], v[24:27], 0
	v_lshl_add_u64 v[16:17], s[22:23], 0, v[16:17]
	v_lshlrev_b64 v[20:21], 11, v[20:21]
	v_lshl_add_u64 v[18:19], v[16:17], 0, v[62:63]
	v_mfma_f32_16x16x32_bf16 v[24:27], v[54:57], v[24:27], 0
	v_lshl_add_u64 v[20:21], s[22:23], 0, v[20:21]
	global_store_short v[18:19], v22, off offset:1024
	v_lshl_add_u64 v[22:23], v[20:21], 0, v[62:63]
	global_store_short v[22:23], v4, off offset:1024
	v_mul_f32_e32 v4, v86, v5
	v_mfma_f32_16x16x32_bf16 v[50:53], v[38:41], v[0:3], v[50:53]
	v_ashrrev_i32_e32 v33, 31, v32
	v_mul_f32_e32 v6, v86, v6
	s_waitcnt vmcnt(5)
	v_mul_f32_e32 v8, v85, v8
	v_mfma_f32_16x16x32_bf16 v[0:3], v[58:61], v[0:3], v[24:27]
	v_cvt_pk_bf16_f32 v6, v6, s0
	v_cvt_pk_bf16_f32 v8, v8, s0
	global_store_short v[22:23], v8, off offset:1056
	v_cvt_pk_bf16_f32 v26, v4, s0
	v_or_b32_e32 v4, 17, v64
	v_ashrrev_i32_e32 v5, 31, v4
	v_lshlrev_b64 v[4:5], 11, v[4:5]
	v_lshl_add_u64 v[4:5], s[22:23], 0, v[4:5]
	v_lshl_add_u64 v[24:25], v[4:5], 0, v[62:63]
	v_mfma_f32_16x16x32_bf16 v[34:37], v[34:37], v[28:31], 0
	global_store_short v[24:25], v26, off offset:1024
	v_or_b32_e32 v26, 18, v64
	v_ashrrev_i32_e32 v27, 31, v26
	v_mfma_f32_16x16x32_bf16 v[28:31], v[54:57], v[28:31], 0
	v_lshlrev_b64 v[26:27], 11, v[26:27]
	v_lshl_add_u64 v[26:27], s[22:23], 0, v[26:27]
	v_lshlrev_b64 v[56:57], 11, v[32:33]
	v_mfma_f32_16x16x32_bf16 v[32:35], v[38:41], v[12:15], v[34:37]
	v_mul_f32_e32 v8, v85, v9
	v_cvt_pk_bf16_f32 v8, v8, s0
	global_store_short v[24:25], v8, off offset:1056
	v_mfma_f32_16x16x32_bf16 v[12:15], v[58:61], v[12:15], v[28:31]
	v_mul_f32_e32 v8, v85, v10
	v_cvt_pk_bf16_f32 v8, v8, s0
	s_waitcnt vmcnt(7)
	v_mul_f32_e32 v0, v84, v0
	v_lshl_add_u64 v[28:29], v[26:27], 0, v[62:63]
	global_store_short v[28:29], v6, off offset:1024
	v_mul_f32_e32 v6, v86, v7
	v_cvt_pk_bf16_f32 v40, v6, s0
	v_or_b32_e32 v6, 19, v64
	v_ashrrev_i32_e32 v7, 31, v6
	v_lshlrev_b64 v[6:7], 11, v[6:7]
	v_lshl_add_u64 v[6:7], s[22:23], 0, v[6:7]
	global_store_short v[28:29], v8, off offset:1056
	v_mul_f32_e32 v8, v85, v11
	v_cvt_pk_bf16_f32 v0, v0, s0
	v_lshl_add_u64 v[30:31], v[6:7], 0, v[62:63]
	v_cvt_pk_bf16_f32 v8, v8, s0
	global_store_short v[22:23], v0, off offset:1088
	v_mul_f32_e32 v0, v84, v1
	global_store_short v[30:31], v8, off offset:1056
	v_mul_f32_e32 v8, v84, v50
	v_cvt_pk_bf16_f32 v0, v0, s0
	global_store_short v[30:31], v40, off offset:1024
	v_mul_f32_e32 v40, v85, v46
	v_cvt_pk_bf16_f32 v8, v8, s0
	global_store_short v[24:25], v0, off offset:1088
	v_mul_f32_e32 v0, v84, v2
	v_cvt_pk_bf16_f32 v40, v40, s0
	global_store_short v[68:69], v8, off offset:1088
	v_mul_f32_e32 v8, v84, v51
	v_cvt_pk_bf16_f32 v0, v0, s0
	v_lshl_add_u64 v[54:55], v[42:43], 0, v[62:63]
	global_store_short v[68:69], v40, off offset:1056
	v_mul_f32_e32 v40, v85, v47
	v_cvt_pk_bf16_f32 v8, v8, s0
	global_store_short v[28:29], v0, off offset:1088
	v_mul_f32_e32 v0, v84, v3
	v_lshl_add_u64 v[36:37], s[22:23], 0, v[56:57]
	v_cvt_pk_bf16_f32 v40, v40, s0
	global_store_short v[54:55], v8, off offset:1088
	v_mul_f32_e32 v8, v84, v52
	v_cvt_pk_bf16_f32 v0, v0, s0
	v_lshl_add_u64 v[38:39], v[36:37], 0, v[62:63]
	global_store_short v[54:55], v40, off offset:1056
	v_mul_f32_e32 v40, v85, v48
	v_cvt_pk_bf16_f32 v8, v8, s0
	global_store_short v[30:31], v0, off offset:1088
	v_or_b32_e32 v0, 48, v82
	v_cvt_pk_bf16_f32 v40, v40, s0
	global_store_short v[38:39], v8, off offset:1088
	v_mul_f32_e32 v8, v84, v53
	v_ashrrev_i32_e32 v1, 31, v0
	global_store_short v[38:39], v40, off offset:1056
	v_mul_f32_e32 v40, v85, v49
	v_cvt_pk_bf16_f32 v8, v8, s0
	s_waitcnt vmcnt(20)
	v_mul_f32_e32 v2, v83, v32
	v_lshlrev_b64 v[0:1], 1, v[0:1]
	v_cvt_pk_bf16_f32 v40, v40, s0
	global_store_short v[18:19], v8, off offset:1088
	v_cvt_pk_bf16_f32 v8, v2, s0
	v_lshl_add_u64 v[2:3], v[66:67], 0, v[0:1]
	global_store_short v[54:55], v65, off offset:1024
	global_store_short v[38:39], v44, off offset:1024
	global_store_short v[18:19], v40, off offset:1056
	global_store_short v[2:3], v8, off offset:1024
	v_mul_f32_e32 v2, v83, v33
	v_cvt_pk_bf16_f32 v8, v2, s0
	v_lshl_add_u64 v[2:3], v[42:43], 0, v[0:1]
	global_store_short v[2:3], v8, off offset:1024
	v_mul_f32_e32 v2, v83, v34
	v_cvt_pk_bf16_f32 v8, v2, s0
	v_lshl_add_u64 v[2:3], v[36:37], 0, v[0:1]
	global_store_short v[2:3], v8, off offset:1024
	v_mul_f32_e32 v2, v83, v35
	v_cvt_pk_bf16_f32 v8, v2, s0
	v_lshl_add_u64 v[2:3], v[16:17], 0, v[0:1]
	global_store_short v[2:3], v8, off offset:1024
	v_mul_f32_e32 v2, v83, v12
	v_cvt_pk_bf16_f32 v8, v2, s0
	v_lshl_add_u64 v[2:3], v[20:21], 0, v[0:1]
	global_store_short v[2:3], v8, off offset:1024
	v_mul_f32_e32 v2, v83, v13
	v_cvt_pk_bf16_f32 v8, v2, s0
	v_lshl_add_u64 v[2:3], v[4:5], 0, v[0:1]
	global_store_short v[2:3], v8, off offset:1024
	v_mul_f32_e32 v2, v83, v14
	v_cvt_pk_bf16_f32 v4, v2, s0
	v_lshl_add_u64 v[2:3], v[26:27], 0, v[0:1]
	s_bfe_u32 s3, s2, 0x20001
	s_lshl_b32 s28, s29, 7
	global_store_short v[2:3], v4, off offset:1024
	v_mul_f32_e32 v2, v83, v15
	s_cmp_gt_i32 s29, 31
	v_cvt_pk_bf16_f32 v2, v2, s0
	s_cselect_b64 s[0:1], -1, 0
	s_or_b32 s38, s3, s79
	s_ashr_i32 s39, s38, 31
	v_readlane_b32 s40, v253, 3
	s_lshl_b64 s[38:39], s[38:39], 2
	v_readlane_b32 s48, v253, 11
	v_readlane_b32 s49, v253, 12
	s_add_u32 s38, s48, s38
	v_lshl_add_u64 v[0:1], v[6:7], 0, v[0:1]
	v_readlane_b32 s41, v253, 4
	s_addc_u32 s39, s49, s39
	s_mul_i32 s40, s29, 0xb0000
	global_store_short v[0:1], v2, off offset:1024
	v_mov_b32_e32 v38, v229
	v_readlane_b32 s42, v253, 5
	s_mul_hi_i32 s41, s28, 0x1600
	s_add_u32 s40, s20, s40
	v_mov_b32_e32 v22, v229
	s_waitcnt lgkmcnt(0)
	s_barrier
	s_addc_u32 s41, s21, s41
	s_lshl_b32 s42, s3, 7
	global_load_dword v41, v201, s[38:39]
	s_add_u32 s40, s40, s42
	v_lshlrev_b32_e32 v0, 2, v22
	v_and_b32_e32 v23, 60, v0
	s_addc_u32 s41, s41, 0
	v_lshlrev_b32_e32 v200, 1, v23
	v_lshl_add_u64 v[0:1], s[40:41], 0, v[200:201]
	s_mov_b64 s[38:39], 0x1200
	v_lshl_add_u64 v[0:1], v[0:1], 0, s[38:39]
	v_ashrrev_i32_e32 v2, 4, v22
	v_mad_i64_i32 v[2:3], s[38:39], v2, s92, v[0:1]
	global_load_dwordx2 v[2:3], v[2:3], off
	v_add_u32_e32 v24, 0x100, v22
	v_ashrrev_i32_e32 v4, 4, v24
	v_mad_i64_i32 v[4:5], s[38:39], v4, s92, v[0:1]
	global_load_dwordx2 v[4:5], v[4:5], off
	v_add_u32_e32 v25, 0x200, v22
	v_ashrrev_i32_e32 v6, 4, v25
	v_mad_i64_i32 v[6:7], s[38:39], v6, s92, v[0:1]
	global_load_dwordx2 v[6:7], v[6:7], off
	v_add_u32_e32 v26, 0x300, v22
	v_ashrrev_i32_e32 v8, 4, v26
	v_mad_i64_i32 v[8:9], s[38:39], v8, s92, v[0:1]
	global_load_dwordx2 v[8:9], v[8:9], off
	v_add_u32_e32 v27, 0x400, v22
	v_ashrrev_i32_e32 v10, 4, v27
	v_mad_i64_i32 v[10:11], s[38:39], v10, s92, v[0:1]
	global_load_dwordx2 v[10:11], v[10:11], off
	v_add_u32_e32 v28, 0x500, v22
	s_lshl_b32 s40, s80, 1
	v_ashrrev_i32_e32 v12, 4, v28
	s_or_b32 s38, s42, s40
	v_mad_i64_i32 v[12:13], s[40:41], v12, s92, v[0:1]
	s_add_u32 s38, s20, s38
	global_load_dwordx2 v[12:13], v[12:13], off
	v_add_u32_e32 v29, 0x600, v22
	v_add_u32_e32 v30, 0x700, v22
	v_bfe_u32 v31, v38, 2, 1
	s_addc_u32 s39, s21, 0
	v_ashrrev_i32_e32 v14, 4, v29
	v_ashrrev_i32_e32 v16, 4, v30
	v_lshlrev_b32_e32 v200, 6, v31
	v_lshlrev_b32_e32 v39, 3, v38
	v_mad_i64_i32 v[14:15], s[40:41], v14, s92, v[0:1]
	v_mad_i64_i32 v[0:1], s[40:41], v16, s92, v[0:1]
	v_lshl_add_u64 v[16:17], s[38:39], 0, v[200:201]
	v_and_b32_e32 v200, 24, v39
	v_ashrrev_i32_e32 v40, 3, v38
	global_load_dwordx2 v[14:15], v[14:15], off
	v_lshl_add_u64 v[16:17], v[16:17], 0, v[200:201]
	v_add_u32_e32 v18, s28, v40
	v_mad_i64_i32 v[18:19], s[38:39], v18, s92, v[16:17]
	global_load_dwordx2 v[0:1], v[0:1], off
	s_nop 0
	global_load_dwordx2 v[20:21], v[18:19], off
	s_nop 0
	global_load_dwordx2 v[18:19], v[18:19], off offset:32
	s_cmp_lt_i32 s29, 32
	v_mov_b32_e32 v32, s69
	s_movk_i32 s29, 0x110
	v_ashrrev_i32_e32 v22, 3, v22
	v_mad_u32_u24 v23, v23, s29, v32
	v_and_b32_e32 v22, -2, v22
	v_add_u32_e32 v22, v23, v22
	v_add_u32_e32 v54, 0x100, v38
	v_ashrrev_i32_e32 v42, 3, v54
	v_add_u32_e32 v46, s28, v42
	v_mad_i64_i32 v[48:49], vcc, v46, s92, v[16:17]
	global_load_dwordx2 v[60:61], v[48:49], off
	global_load_dwordx2 v[62:63], v[48:49], off offset:32
	v_add_u32_e32 v55, 0x200, v38
	v_ashrrev_i32_e32 v43, 3, v55
	v_add_u32_e32 v46, s28, v43
	v_mad_i64_i32 v[48:49], vcc, v46, s92, v[16:17]
	global_load_dwordx2 v[64:65], v[48:49], off
	global_load_dwordx2 v[66:67], v[48:49], off offset:32
	v_add_u32_e32 v56, 0x300, v38
	v_ashrrev_i32_e32 v44, 3, v56
	v_add_u32_e32 v46, s28, v44
	v_mad_i64_i32 v[48:49], vcc, v46, s92, v[16:17]
	global_load_dwordx2 v[68:69], v[48:49], off
	global_load_dwordx2 v[70:71], v[48:49], off offset:32
	s_waitcnt vmcnt(15)
	ds_write_b16 v22, v2 offset:17408
	ds_write_b16_d16_hi v22, v2 offset:17680
	ds_write_b16 v22, v3 offset:17952
	ds_write_b16_d16_hi v22, v3 offset:18224
	v_ashrrev_i32_e32 v2, 3, v24
	v_and_b32_e32 v2, -2, v2
	v_add_u32_e32 v2, v23, v2
	s_waitcnt vmcnt(14)
	ds_write_b16 v2, v4 offset:17408
	ds_write_b16_d16_hi v2, v4 offset:17680
	ds_write_b16 v2, v5 offset:17952
	ds_write_b16_d16_hi v2, v5 offset:18224
	v_ashrrev_i32_e32 v2, 3, v25
	v_and_b32_e32 v2, -2, v2
	v_add_u32_e32 v2, v23, v2
	s_waitcnt vmcnt(13)
	ds_write_b16 v2, v6 offset:17408
	ds_write_b16_d16_hi v2, v6 offset:17680
	ds_write_b16 v2, v7 offset:17952
	ds_write_b16_d16_hi v2, v7 offset:18224
	v_ashrrev_i32_e32 v2, 3, v26
	v_and_b32_e32 v2, -2, v2
	v_add_u32_e32 v2, v23, v2
	s_waitcnt vmcnt(12)
	ds_write_b16 v2, v8 offset:17408
	ds_write_b16_d16_hi v2, v8 offset:17680
	ds_write_b16 v2, v9 offset:17952
	ds_write_b16_d16_hi v2, v9 offset:18224
	v_ashrrev_i32_e32 v2, 3, v27
	v_and_b32_e32 v2, -2, v2
	v_add_u32_e32 v2, v23, v2
	s_waitcnt vmcnt(11)
	ds_write_b16 v2, v10 offset:17408
	ds_write_b16_d16_hi v2, v10 offset:17680
	ds_write_b16 v2, v11 offset:17952
	ds_write_b16_d16_hi v2, v11 offset:18224
	v_ashrrev_i32_e32 v2, 3, v28
	v_and_b32_e32 v2, -2, v2
	v_add_u32_e32 v2, v23, v2
	s_waitcnt vmcnt(10)
	ds_write_b16 v2, v12 offset:17408
	ds_write_b16_d16_hi v2, v12 offset:17680
	ds_write_b16 v2, v13 offset:17952
	ds_write_b16_d16_hi v2, v13 offset:18224
	v_ashrrev_i32_e32 v2, 3, v29
	v_and_b32_e32 v2, -2, v2
	s_cselect_b64 s[40:41], -1, 0
	v_add_u32_e32 v2, v23, v2
	s_waitcnt vmcnt(9)
	ds_write_b16 v2, v14 offset:17408
	ds_write_b16_d16_hi v2, v14 offset:17680
	ds_write_b16 v2, v15 offset:17952
	ds_write_b16_d16_hi v2, v15 offset:18224
	v_ashrrev_i32_e32 v2, 3, v30
	s_and_b64 vcc, s[40:41], exec
	s_mov_b32 s29, 0x80000380
	v_and_b32_e32 v2, -2, v2
	s_cselect_b32 s29, 0x80, s29
	v_add_u32_e32 v2, v23, v2
	v_cmp_eq_u32_e64 s[38:39], 0, v31
	s_and_b32 s29, s29, s28
	s_waitcnt vmcnt(7)
	v_lshlrev_b32_e32 v12, 16, v20
	v_and_b32_e32 v13, 0xffff0000, v20
	v_lshlrev_b32_e32 v15, 16, v21
	s_waitcnt vmcnt(6)
	v_lshlrev_b32_e32 v8, 16, v18
	v_and_b32_e32 v9, 0xffff0000, v18
	v_lshlrev_b32_e32 v14, 16, v19
	v_and_b32_e32 v11, 0xffff0000, v19
	v_and_b32_e32 v10, 0xffff0000, v21
	s_mov_b64 s[40:41], -1
	v_readlane_b32 s43, v253, 6
	v_readlane_b32 s44, v253, 7
	v_readlane_b32 s45, v253, 8
	v_readlane_b32 s46, v253, 9
	v_readlane_b32 s47, v253, 10
	v_readlane_b32 s50, v253, 13
	v_readlane_b32 s51, v253, 14
	v_readlane_b32 s52, v253, 15
	v_readlane_b32 s53, v253, 16
	v_readlane_b32 s54, v253, 17
	v_readlane_b32 s55, v253, 18
	ds_write_b16 v2, v0 offset:17408
	ds_write_b16_d16_hi v2, v0 offset:17680
	ds_write_b16 v2, v1 offset:17952
	ds_write_b16_d16_hi v2, v1 offset:18224
	s_and_b64 vcc, exec, s[0:1]
	s_cbranch_vccz .Lkv_norot_a
	v_add_u32_e32 v32, s29, v40
	v_ashrrev_i32_e32 v32, 6, v32
	v_bfe_u32 v33, v38, 3, 6
	v_cndmask_b32_e64 v32, v33, v32, s[38:39]
	v_lshl_or_b32 v32, v32, 5, v200
	v_lshlrev_b32_e32 v50, 2, v32
	global_load_dwordx4 v[72:75], v50, s[12:13]
	global_load_dwordx4 v[76:79], v50, s[12:13] offset:16
	v_add_u32_e32 v32, s29, v42
	v_ashrrev_i32_e32 v32, 6, v32
	v_bfe_u32 v33, v54, 3, 6
	v_cndmask_b32_e64 v32, v33, v32, s[38:39]
	v_lshl_or_b32 v32, v32, 5, v200
	v_lshlrev_b32_e32 v51, 2, v32
	global_load_dwordx4 v[80:83], v51, s[12:13]
	global_load_dwordx4 v[84:87], v51, s[12:13] offset:16
	v_add_u32_e32 v32, s29, v43
	v_ashrrev_i32_e32 v32, 6, v32
	v_bfe_u32 v33, v55, 3, 6
	v_cndmask_b32_e64 v32, v33, v32, s[38:39]
	v_lshl_or_b32 v32, v32, 5, v200
	v_lshlrev_b32_e32 v52, 2, v32
	global_load_dwordx4 v[88:91], v52, s[12:13]
	global_load_dwordx4 v[92:95], v52, s[12:13] offset:16
	v_add_u32_e32 v32, s29, v44
	v_ashrrev_i32_e32 v32, 6, v32
	v_bfe_u32 v33, v56, 3, 6
	v_cndmask_b32_e64 v32, v33, v32, s[38:39]
	v_lshl_or_b32 v32, v32, 5, v200
	v_lshlrev_b32_e32 v53, 2, v32
	global_load_dwordx4 v[96:99], v53, s[12:13]
	global_load_dwordx4 v[100:103], v53, s[12:13] offset:16
	s_waitcnt vmcnt(0)
	v_mul_f32_e32 v34, v8, v73
	v_mul_f32_e32 v35, v12, v73
	v_fma_f32 v0, v12, v72, -v34
	v_fma_f32 v6, v8, v72, v35
	v_mul_f32_e32 v34, v9, v75
	v_mul_f32_e32 v35, v13, v75
	v_fma_f32 v1, v13, v74, -v34
	v_fma_f32 v7, v9, v74, v35
	v_mul_f32_e32 v34, v14, v77
	v_mul_f32_e32 v35, v15, v77
	v_fma_f32 v2, v15, v76, -v34
	v_fma_f32 v4, v14, v76, v35
	v_mul_f32_e32 v34, v11, v79
	v_mul_f32_e32 v35, v10, v79
	v_fma_f32 v3, v10, v78, -v34
	v_fma_f32 v5, v11, v78, v35
	v_lshlrev_b32_e32 v32, 16, v60
	v_lshlrev_b32_e32 v33, 16, v62
	v_mul_f32_e32 v34, v33, v81
	v_mul_f32_e32 v35, v32, v81
	v_fma_f32 v8, v32, v80, -v34
	v_fma_f32 v14, v33, v80, v35
	v_and_b32_e32 v32, 0xffff0000, v60
	v_and_b32_e32 v33, 0xffff0000, v62
	v_mul_f32_e32 v34, v33, v83
	v_mul_f32_e32 v35, v32, v83
	v_fma_f32 v9, v32, v82, -v34
	v_fma_f32 v15, v33, v82, v35
	v_lshlrev_b32_e32 v32, 16, v61
	v_lshlrev_b32_e32 v33, 16, v63
	v_mul_f32_e32 v34, v33, v85
	v_mul_f32_e32 v35, v32, v85
	v_fma_f32 v10, v32, v84, -v34
	v_fma_f32 v12, v33, v84, v35
	v_and_b32_e32 v32, 0xffff0000, v61
	v_and_b32_e32 v33, 0xffff0000, v63
	v_mul_f32_e32 v34, v33, v87
	v_mul_f32_e32 v35, v32, v87
	v_fma_f32 v11, v32, v86, -v34
	v_fma_f32 v13, v33, v86, v35
	v_lshlrev_b32_e32 v32, 16, v64
	v_lshlrev_b32_e32 v33, 16, v66
	v_mul_f32_e32 v34, v33, v89
	v_mul_f32_e32 v35, v32, v89
	v_fma_f32 v18, v32, v88, -v34
	v_fma_f32 v24, v33, v88, v35
	v_and_b32_e32 v32, 0xffff0000, v64
	v_and_b32_e32 v33, 0xffff0000, v66
	v_mul_f32_e32 v34, v33, v91
	v_mul_f32_e32 v35, v32, v91
	v_fma_f32 v19, v32, v90, -v34
	v_fma_f32 v25, v33, v90, v35
	v_lshlrev_b32_e32 v32, 16, v65
	v_lshlrev_b32_e32 v33, 16, v67
	v_mul_f32_e32 v34, v33, v93
	v_mul_f32_e32 v35, v32, v93
	v_fma_f32 v20, v32, v92, -v34
	v_fma_f32 v22, v33, v92, v35
	v_and_b32_e32 v32, 0xffff0000, v65
	v_and_b32_e32 v33, 0xffff0000, v67
	v_mul_f32_e32 v34, v33, v95
	v_mul_f32_e32 v35, v32, v95
	v_fma_f32 v21, v32, v94, -v34
	v_fma_f32 v23, v33, v94, v35
	v_lshlrev_b32_e32 v32, 16, v68
	v_lshlrev_b32_e32 v33, 16, v70
	v_mul_f32_e32 v34, v33, v97
	v_mul_f32_e32 v35, v32, v97
	v_fma_f32 v16, v32, v96, -v34
	v_fma_f32 v30, v33, v96, v35
	v_and_b32_e32 v32, 0xffff0000, v68
	v_and_b32_e32 v33, 0xffff0000, v70
	v_mul_f32_e32 v34, v33, v99
	v_mul_f32_e32 v35, v32, v99
	v_fma_f32 v17, v32, v98, -v34
	v_fma_f32 v31, v33, v98, v35
	v_lshlrev_b32_e32 v32, 16, v69
	v_lshlrev_b32_e32 v33, 16, v71
	v_mul_f32_e32 v34, v33, v101
	v_mul_f32_e32 v35, v32, v101
	v_fma_f32 v26, v32, v100, -v34
	v_fma_f32 v28, v33, v100, v35
	v_and_b32_e32 v32, 0xffff0000, v69
	v_and_b32_e32 v33, 0xffff0000, v71
	v_mul_f32_e32 v34, v33, v103
	v_mul_f32_e32 v35, v32, v103
	v_fma_f32 v27, v32, v102, -v34
	v_fma_f32 v29, v33, v102, v35
	s_branch .Lkv_done_a

.LBB0_521:
	s_or_b64 exec, exec, s[0:1]
	s_waitcnt lgkmcnt(0)
	s_barrier
	v_lshl_add_u32 v40, v122, 2, s69
	ds_read2st64_b32 v[10:11], v40 offset1:4
	ds_read2st64_b32 v[14:15], v40 offset0:8 offset1:12
	ds_read2st64_b32 v[20:21], v40 offset0:16 offset1:20
	ds_read2st64_b32 v[12:13], v40 offset0:112 offset1:116
	ds_read2st64_b32 v[24:25], v40 offset0:24 offset1:28
	s_waitcnt lgkmcnt(4)
	v_fma_f32 v41, v108, v10, v75
	ds_read2st64_b32 v[28:29], v40 offset0:32 offset1:36
	ds_read2st64_b32 v[32:33], v40 offset0:40 offset1:44
	ds_read2st64_b32 v[36:37], v40 offset0:48 offset1:52
	ds_read2st64_b32 v[38:39], v40 offset0:56 offset1:60
	ds_read2st64_b32 v[34:35], v40 offset0:64 offset1:68
	ds_read2st64_b32 v[30:31], v40 offset0:72 offset1:76
	ds_read2st64_b32 v[26:27], v40 offset0:80 offset1:84
	ds_read2st64_b32 v[22:23], v40 offset0:88 offset1:92
	ds_read2st64_b32 v[18:19], v40 offset0:96 offset1:100
	ds_read2st64_b32 v[16:17], v40 offset0:104 offset1:108
	ds_read2st64_b32 v[8:9], v40 offset0:120 offset1:124
	v_fma_f32 v42, v108, v11, v75
	v_fmac_f32_e32 v41, v107, v11
	ds_read2st64_b32 v[10:11], v40 offset0:128 offset1:132
	s_waitcnt lgkmcnt(14)
	v_fma_f32 v43, v108, v14, v75
	v_fmac_f32_e32 v42, v107, v14
	v_fmac_f32_e32 v41, v106, v14
	v_fma_f32 v44, v108, v15, v75
	v_fma_f32 v45, v108, v20, v75
	v_fmac_f32_e32 v43, v107, v15
	v_fmac_f32_e32 v42, v106, v15
	v_fmac_f32_e32 v41, v103, v15
	ds_read2st64_b32 v[14:15], v40 offset0:136 offset1:140
	v_fma_f32 v46, v108, v21, v75
	s_waitcnt lgkmcnt(14)
	v_fma_f32 v69, v108, v12, v75
	v_fmac_f32_e32 v44, v107, v20
	v_fmac_f32_e32 v45, v107, v21
	v_fmac_f32_e32 v43, v106, v20
	v_fmac_f32_e32 v42, v103, v20
	v_fmac_f32_e32 v41, v101, v20
	s_waitcnt lgkmcnt(13)
	v_fma_f32 v47, v108, v24, v75
	v_fma_f32 v48, v108, v25, v75
	s_waitcnt lgkmcnt(12)
	v_fma_f32 v49, v108, v28, v75
	v_fma_f32 v50, v108, v29, v75
	s_waitcnt lgkmcnt(11)
	v_fma_f32 v51, v108, v32, v75
	v_fma_f32 v52, v108, v33, v75
	s_waitcnt lgkmcnt(10)
	v_fma_f32 v53, v108, v36, v75
	v_fma_f32 v54, v108, v37, v75
	s_waitcnt lgkmcnt(9)
	v_fma_f32 v55, v108, v38, v75
	v_fma_f32 v56, v108, v39, v75
	s_waitcnt lgkmcnt(8)
	v_fma_f32 v57, v108, v34, v75
	v_fma_f32 v58, v108, v35, v75
	s_waitcnt lgkmcnt(7)
	v_fma_f32 v59, v108, v30, v75
	v_fma_f32 v60, v108, v31, v75
	s_waitcnt lgkmcnt(6)
	v_fma_f32 v61, v108, v26, v75
	v_fma_f32 v62, v108, v27, v75
	s_waitcnt lgkmcnt(5)
	v_fma_f32 v63, v108, v22, v75
	v_fma_f32 v64, v108, v23, v75
	s_waitcnt lgkmcnt(4)
	v_fma_f32 v65, v108, v18, v75
	v_fma_f32 v66, v108, v19, v75
	s_waitcnt lgkmcnt(3)
	v_fma_f32 v67, v108, v16, v75
	v_fma_f32 v68, v108, v17, v75
	v_fma_f32 v70, v108, v13, v75
	s_waitcnt lgkmcnt(2)
	v_fma_f32 v71, v108, v8, v75
	v_fmac_f32_e32 v75, v108, v9
	v_fmac_f32_e32 v46, v107, v24
	v_fmac_f32_e32 v69, v107, v13
	v_fmac_f32_e32 v44, v106, v21
	v_fmac_f32_e32 v45, v106, v24
	v_fmac_f32_e32 v43, v103, v21
	v_fmac_f32_e32 v42, v101, v21
	v_fmac_f32_e32 v41, v100, v21
	ds_read2st64_b32 v[20:21], v40 offset0:144 offset1:148
	v_fmac_f32_e32 v47, v107, v25
	v_fmac_f32_e32 v48, v107, v28
	v_fmac_f32_e32 v49, v107, v29
	v_fmac_f32_e32 v50, v107, v32
	v_fmac_f32_e32 v51, v107, v33
	v_fmac_f32_e32 v52, v107, v36
	v_fmac_f32_e32 v53, v107, v37
	v_fmac_f32_e32 v54, v107, v38
	v_fmac_f32_e32 v55, v107, v39
	v_fmac_f32_e32 v56, v107, v34
	v_fmac_f32_e32 v57, v107, v35
	v_fmac_f32_e32 v58, v107, v30
	v_fmac_f32_e32 v59, v107, v31
	v_fmac_f32_e32 v60, v107, v26
	v_fmac_f32_e32 v61, v107, v27
	v_fmac_f32_e32 v62, v107, v22
	v_fmac_f32_e32 v63, v107, v23
	v_fmac_f32_e32 v64, v107, v18
	v_fmac_f32_e32 v65, v107, v19
	v_fmac_f32_e32 v66, v107, v16
	v_fmac_f32_e32 v67, v107, v17
	v_fmac_f32_e32 v68, v107, v12
	v_fmac_f32_e32 v70, v107, v8
	v_fmac_f32_e32 v71, v107, v9
	s_waitcnt lgkmcnt(2)
	v_fmac_f32_e32 v75, v107, v10
	v_fmac_f32_e32 v46, v106, v25
	v_fmac_f32_e32 v69, v106, v8
	v_fmac_f32_e32 v44, v103, v24
	v_fmac_f32_e32 v45, v103, v25
	v_fmac_f32_e32 v43, v101, v24
	v_fmac_f32_e32 v42, v100, v24
	v_fmac_f32_e32 v41, v99, v24
	v_fmac_f32_e32 v47, v106, v28
	v_fmac_f32_e32 v48, v106, v29
	v_fmac_f32_e32 v49, v106, v32
	v_fmac_f32_e32 v50, v106, v33
	v_fmac_f32_e32 v51, v106, v36
	v_fmac_f32_e32 v52, v106, v37
	v_fmac_f32_e32 v53, v106, v38
	v_fmac_f32_e32 v54, v106, v39
	v_fmac_f32_e32 v55, v106, v34
	v_fmac_f32_e32 v56, v106, v35
	v_fmac_f32_e32 v57, v106, v30
	v_fmac_f32_e32 v58, v106, v31
	v_fmac_f32_e32 v59, v106, v26
	v_fmac_f32_e32 v60, v106, v27
	v_fmac_f32_e32 v61, v106, v22
	v_fmac_f32_e32 v62, v106, v23
	v_fmac_f32_e32 v63, v106, v18
	v_fmac_f32_e32 v64, v106, v19
	v_fmac_f32_e32 v65, v106, v16
	v_fmac_f32_e32 v66, v106, v17
	v_fmac_f32_e32 v67, v106, v12
	v_fmac_f32_e32 v68, v106, v13
	v_fmac_f32_e32 v70, v106, v9
	v_fmac_f32_e32 v71, v106, v10
	v_fmac_f32_e32 v75, v106, v11
	v_fmac_f32_e32 v46, v103, v28
	v_fmac_f32_e32 v69, v103, v9
	v_fmac_f32_e32 v44, v101, v25
	v_fmac_f32_e32 v45, v101, v28
	v_fmac_f32_e32 v43, v100, v25
	v_fmac_f32_e32 v42, v99, v25
	v_fmac_f32_e32 v41, v98, v25
	ds_read2st64_b32 v[24:25], v40 offset0:152 offset1:156
	v_fmac_f32_e32 v47, v103, v29
	v_fmac_f32_e32 v48, v103, v32
	v_fmac_f32_e32 v49, v103, v33
	v_fmac_f32_e32 v50, v103, v36
	v_fmac_f32_e32 v51, v103, v37
	v_fmac_f32_e32 v52, v103, v38
	v_fmac_f32_e32 v53, v103, v39
	v_fmac_f32_e32 v54, v103, v34
	v_fmac_f32_e32 v55, v103, v35
	v_fmac_f32_e32 v56, v103, v30
	v_fmac_f32_e32 v57, v103, v31
	v_fmac_f32_e32 v58, v103, v26
	v_fmac_f32_e32 v59, v103, v27
	v_fmac_f32_e32 v60, v103, v22
	v_fmac_f32_e32 v61, v103, v23
	v_fmac_f32_e32 v62, v103, v18
	v_fmac_f32_e32 v63, v103, v19
	v_fmac_f32_e32 v64, v103, v16
	v_fmac_f32_e32 v65, v103, v17
	v_fmac_f32_e32 v66, v103, v12
	v_fmac_f32_e32 v67, v103, v13
	v_fmac_f32_e32 v68, v103, v8
	v_fmac_f32_e32 v70, v103, v10
	v_fmac_f32_e32 v71, v103, v11
	s_waitcnt lgkmcnt(2)
	v_fmac_f32_e32 v75, v103, v14
	v_fmac_f32_e32 v46, v101, v29
	v_fmac_f32_e32 v69, v101, v10
	v_fmac_f32_e32 v44, v100, v28
	v_fmac_f32_e32 v45, v100, v29
	v_fmac_f32_e32 v43, v99, v28
	v_fmac_f32_e32 v42, v98, v28
	v_fmac_f32_e32 v41, v97, v28
	v_fmac_f32_e32 v47, v101, v32
	v_fmac_f32_e32 v48, v101, v33
	v_fmac_f32_e32 v49, v101, v36
	v_fmac_f32_e32 v50, v101, v37
	v_fmac_f32_e32 v51, v101, v38
	v_fmac_f32_e32 v52, v101, v39
	v_fmac_f32_e32 v53, v101, v34
	v_fmac_f32_e32 v54, v101, v35
	v_fmac_f32_e32 v55, v101, v30
	v_fmac_f32_e32 v56, v101, v31
	v_fmac_f32_e32 v57, v101, v26
	v_fmac_f32_e32 v58, v101, v27
	v_fmac_f32_e32 v59, v101, v22
	v_fmac_f32_e32 v60, v101, v23
	v_fmac_f32_e32 v61, v101, v18
	v_fmac_f32_e32 v62, v101, v19
	v_fmac_f32_e32 v63, v101, v16
	v_fmac_f32_e32 v64, v101, v17
	v_fmac_f32_e32 v65, v101, v12
	v_fmac_f32_e32 v66, v101, v13
	v_fmac_f32_e32 v67, v101, v8
	v_fmac_f32_e32 v68, v101, v9
	v_fmac_f32_e32 v70, v101, v11
	v_fmac_f32_e32 v71, v101, v14
	v_fmac_f32_e32 v75, v101, v15
	v_fmac_f32_e32 v46, v100, v32
	v_fmac_f32_e32 v69, v100, v11
	v_fmac_f32_e32 v44, v99, v29
	v_fmac_f32_e32 v45, v99, v32
	v_fmac_f32_e32 v43, v98, v29
	v_fmac_f32_e32 v42, v97, v29
	v_fmac_f32_e32 v41, v96, v29
	ds_read2st64_b32 v[28:29], v40 offset0:160 offset1:164
	v_fmac_f32_e32 v47, v100, v33
	v_fmac_f32_e32 v48, v100, v36
	v_fmac_f32_e32 v49, v100, v37
	v_fmac_f32_e32 v50, v100, v38
	v_fmac_f32_e32 v51, v100, v39
	v_fmac_f32_e32 v52, v100, v34
	v_fmac_f32_e32 v53, v100, v35
	v_fmac_f32_e32 v54, v100, v30
	v_fmac_f32_e32 v55, v100, v31
	v_fmac_f32_e32 v56, v100, v26
	v_fmac_f32_e32 v57, v100, v27
	v_fmac_f32_e32 v58, v100, v22
	v_fmac_f32_e32 v59, v100, v23
	v_fmac_f32_e32 v60, v100, v18
	v_fmac_f32_e32 v61, v100, v19
	v_fmac_f32_e32 v62, v100, v16
	v_fmac_f32_e32 v63, v100, v17
	v_fmac_f32_e32 v64, v100, v12
	v_fmac_f32_e32 v65, v100, v13
	v_fmac_f32_e32 v66, v100, v8
	v_fmac_f32_e32 v67, v100, v9
	v_fmac_f32_e32 v68, v100, v10
	v_fmac_f32_e32 v70, v100, v14
	v_fmac_f32_e32 v71, v100, v15
	s_waitcnt lgkmcnt(2)
	v_fmac_f32_e32 v75, v100, v20
	v_fmac_f32_e32 v46, v99, v33
	v_fmac_f32_e32 v69, v99, v14
	v_fmac_f32_e32 v44, v98, v32
	v_fmac_f32_e32 v45, v98, v33
	v_fmac_f32_e32 v43, v97, v32
	v_fmac_f32_e32 v42, v96, v32
	v_fmac_f32_e32 v41, v95, v32
	v_fmac_f32_e32 v47, v99, v36
	v_fmac_f32_e32 v48, v99, v37
	v_fmac_f32_e32 v49, v99, v38
	v_fmac_f32_e32 v50, v99, v39
	v_fmac_f32_e32 v51, v99, v34
	v_fmac_f32_e32 v52, v99, v35
	v_fmac_f32_e32 v53, v99, v30
	v_fmac_f32_e32 v54, v99, v31
	v_fmac_f32_e32 v55, v99, v26
	v_fmac_f32_e32 v56, v99, v27
	v_fmac_f32_e32 v57, v99, v22
	v_fmac_f32_e32 v58, v99, v23
	v_fmac_f32_e32 v59, v99, v18
	v_fmac_f32_e32 v60, v99, v19
	v_fmac_f32_e32 v61, v99, v16
	v_fmac_f32_e32 v62, v99, v17
	v_fmac_f32_e32 v63, v99, v12
	v_fmac_f32_e32 v64, v99, v13
	v_fmac_f32_e32 v65, v99, v8
	v_fmac_f32_e32 v66, v99, v9
	v_fmac_f32_e32 v67, v99, v10
	v_fmac_f32_e32 v68, v99, v11
	v_fmac_f32_e32 v70, v99, v15
	v_fmac_f32_e32 v71, v99, v20
	v_fmac_f32_e32 v75, v99, v21
	v_fmac_f32_e32 v46, v98, v36
	v_fmac_f32_e32 v69, v98, v15
	v_fmac_f32_e32 v44, v97, v33
	v_fmac_f32_e32 v45, v97, v36
	v_fmac_f32_e32 v43, v96, v33
	v_fmac_f32_e32 v42, v95, v33
	v_fmac_f32_e32 v41, v94, v33
	ds_read2st64_b32 v[32:33], v40 offset0:168 offset1:172
	v_fmac_f32_e32 v47, v98, v37
	v_fmac_f32_e32 v48, v98, v38
	v_fmac_f32_e32 v49, v98, v39
	v_fmac_f32_e32 v50, v98, v34
	v_fmac_f32_e32 v51, v98, v35
	v_fmac_f32_e32 v52, v98, v30
	v_fmac_f32_e32 v53, v98, v31
	v_fmac_f32_e32 v54, v98, v26
	v_fmac_f32_e32 v55, v98, v27
	v_fmac_f32_e32 v56, v98, v22
	v_fmac_f32_e32 v57, v98, v23
	v_fmac_f32_e32 v58, v98, v18
	v_fmac_f32_e32 v59, v98, v19
	v_fmac_f32_e32 v60, v98, v16
	v_fmac_f32_e32 v61, v98, v17
	v_fmac_f32_e32 v62, v98, v12
	v_fmac_f32_e32 v63, v98, v13
	v_fmac_f32_e32 v64, v98, v8
	v_fmac_f32_e32 v65, v98, v9
	v_fmac_f32_e32 v66, v98, v10
	v_fmac_f32_e32 v67, v98, v11
	v_fmac_f32_e32 v68, v98, v14
	v_fmac_f32_e32 v70, v98, v20
	v_fmac_f32_e32 v71, v98, v21
	s_waitcnt lgkmcnt(2)
	v_fmac_f32_e32 v75, v98, v24
	v_fmac_f32_e32 v46, v97, v37
	v_fmac_f32_e32 v69, v97, v20
	v_fmac_f32_e32 v44, v96, v36
	v_fmac_f32_e32 v45, v96, v37
	v_fmac_f32_e32 v43, v95, v36
	v_fmac_f32_e32 v42, v94, v36
	v_fmac_f32_e32 v41, v93, v36
	v_fmac_f32_e32 v47, v97, v38
	v_fmac_f32_e32 v48, v97, v39
	v_fmac_f32_e32 v49, v97, v34
	v_fmac_f32_e32 v50, v97, v35
	v_fmac_f32_e32 v51, v97, v30
	v_fmac_f32_e32 v52, v97, v31
	v_fmac_f32_e32 v53, v97, v26
	v_fmac_f32_e32 v54, v97, v27
	v_fmac_f32_e32 v55, v97, v22
	v_fmac_f32_e32 v56, v97, v23
	v_fmac_f32_e32 v57, v97, v18
	v_fmac_f32_e32 v58, v97, v19
	v_fmac_f32_e32 v59, v97, v16
	v_fmac_f32_e32 v60, v97, v17
	v_fmac_f32_e32 v61, v97, v12
	v_fmac_f32_e32 v62, v97, v13
	v_fmac_f32_e32 v63, v97, v8
	v_fmac_f32_e32 v64, v97, v9
	v_fmac_f32_e32 v65, v97, v10
	v_fmac_f32_e32 v66, v97, v11
	v_fmac_f32_e32 v67, v97, v14
	v_fmac_f32_e32 v68, v97, v15
	v_fmac_f32_e32 v70, v97, v21
	v_fmac_f32_e32 v71, v97, v24
	v_fmac_f32_e32 v75, v97, v25
	v_fmac_f32_e32 v46, v96, v38
	v_fmac_f32_e32 v69, v96, v21
	v_fmac_f32_e32 v44, v95, v37
	v_fmac_f32_e32 v45, v95, v38
	v_fmac_f32_e32 v43, v94, v37
	v_fmac_f32_e32 v42, v93, v37
	v_fmac_f32_e32 v41, v92, v37
	ds_read2st64_b32 v[36:37], v40 offset0:176 offset1:180
	v_fmac_f32_e32 v47, v96, v39
	v_fmac_f32_e32 v48, v96, v34
	v_fmac_f32_e32 v49, v96, v35
	v_fmac_f32_e32 v50, v96, v30
	v_fmac_f32_e32 v51, v96, v31
	v_fmac_f32_e32 v52, v96, v26
	v_fmac_f32_e32 v53, v96, v27
	v_fmac_f32_e32 v54, v96, v22
	v_fmac_f32_e32 v55, v96, v23
	v_fmac_f32_e32 v56, v96, v18
	v_fmac_f32_e32 v57, v96, v19
	v_fmac_f32_e32 v58, v96, v16
	v_fmac_f32_e32 v59, v96, v17
	v_fmac_f32_e32 v60, v96, v12
	v_fmac_f32_e32 v61, v96, v13
	v_fmac_f32_e32 v62, v96, v8
	v_fmac_f32_e32 v63, v96, v9
	v_fmac_f32_e32 v64, v96, v10
	v_fmac_f32_e32 v65, v96, v11
	v_fmac_f32_e32 v66, v96, v14
	v_fmac_f32_e32 v67, v96, v15
	v_fmac_f32_e32 v68, v96, v20
	v_fmac_f32_e32 v70, v96, v24
	v_fmac_f32_e32 v71, v96, v25
	s_waitcnt lgkmcnt(2)
	v_fmac_f32_e32 v75, v96, v28
	v_fmac_f32_e32 v46, v95, v39
	v_fmac_f32_e32 v69, v95, v24
	v_fmac_f32_e32 v44, v94, v38
	v_fmac_f32_e32 v45, v94, v39
	v_fmac_f32_e32 v43, v93, v38
	v_fmac_f32_e32 v42, v92, v38
	v_fmac_f32_e32 v41, v91, v38
	v_fmac_f32_e32 v47, v95, v34
	v_fmac_f32_e32 v48, v95, v35
	v_fmac_f32_e32 v49, v95, v30
	v_fmac_f32_e32 v50, v95, v31
	v_fmac_f32_e32 v51, v95, v26
	v_fmac_f32_e32 v52, v95, v27
	v_fmac_f32_e32 v53, v95, v22
	v_fmac_f32_e32 v54, v95, v23
	v_fmac_f32_e32 v55, v95, v18
	v_fmac_f32_e32 v56, v95, v19
	v_fmac_f32_e32 v57, v95, v16
	v_fmac_f32_e32 v58, v95, v17
	v_fmac_f32_e32 v59, v95, v12
	v_fmac_f32_e32 v60, v95, v13
	v_fmac_f32_e32 v61, v95, v8
	v_fmac_f32_e32 v62, v95, v9
	v_fmac_f32_e32 v63, v95, v10
	v_fmac_f32_e32 v64, v95, v11
	v_fmac_f32_e32 v65, v95, v14
	v_fmac_f32_e32 v66, v95, v15
	v_fmac_f32_e32 v67, v95, v20
	v_fmac_f32_e32 v68, v95, v21
	v_fmac_f32_e32 v70, v95, v25
	v_fmac_f32_e32 v71, v95, v28
	v_fmac_f32_e32 v75, v95, v29
	v_fmac_f32_e32 v46, v94, v34
	v_fmac_f32_e32 v69, v94, v25
	v_fmac_f32_e32 v44, v93, v39
	v_fmac_f32_e32 v45, v93, v34
	v_fmac_f32_e32 v43, v92, v39
	v_fmac_f32_e32 v42, v91, v39
	v_fmac_f32_e32 v41, v90, v39
	ds_read2st64_b32 v[38:39], v40 offset0:184 offset1:188
	v_fmac_f32_e32 v47, v94, v35
	v_fmac_f32_e32 v48, v94, v30
	v_fmac_f32_e32 v49, v94, v31
	v_fmac_f32_e32 v50, v94, v26
	v_fmac_f32_e32 v51, v94, v27
	v_fmac_f32_e32 v52, v94, v22
	v_fmac_f32_e32 v53, v94, v23
	v_fmac_f32_e32 v54, v94, v18
	v_fmac_f32_e32 v55, v94, v19
	v_fmac_f32_e32 v56, v94, v16
	v_fmac_f32_e32 v57, v94, v17
	v_fmac_f32_e32 v58, v94, v12
	v_fmac_f32_e32 v59, v94, v13
	v_fmac_f32_e32 v60, v94, v8
	v_fmac_f32_e32 v61, v94, v9
	v_fmac_f32_e32 v62, v94, v10
	v_fmac_f32_e32 v63, v94, v11
	v_fmac_f32_e32 v64, v94, v14
	v_fmac_f32_e32 v65, v94, v15
	v_fmac_f32_e32 v66, v94, v20
	v_fmac_f32_e32 v67, v94, v21
	v_fmac_f32_e32 v68, v94, v24
	v_fmac_f32_e32 v70, v94, v28
	v_fmac_f32_e32 v71, v94, v29
	s_waitcnt lgkmcnt(2)
	v_fmac_f32_e32 v75, v94, v32
	v_fmac_f32_e32 v46, v93, v35
	v_fmac_f32_e32 v69, v93, v28
	v_fmac_f32_e32 v44, v92, v34
	v_fmac_f32_e32 v45, v92, v35
	v_fmac_f32_e32 v43, v91, v34
	v_fmac_f32_e32 v42, v90, v34
	v_fmac_f32_e32 v41, v89, v34
	v_fmac_f32_e32 v47, v93, v30
	v_fmac_f32_e32 v48, v93, v31
	v_fmac_f32_e32 v49, v93, v26
	v_fmac_f32_e32 v50, v93, v27
	v_fmac_f32_e32 v51, v93, v22
	v_fmac_f32_e32 v52, v93, v23
	v_fmac_f32_e32 v53, v93, v18
	v_fmac_f32_e32 v54, v93, v19
	v_fmac_f32_e32 v55, v93, v16
	v_fmac_f32_e32 v56, v93, v17
	v_fmac_f32_e32 v57, v93, v12
	v_fmac_f32_e32 v58, v93, v13
	v_fmac_f32_e32 v59, v93, v8
	v_fmac_f32_e32 v60, v93, v9
	v_fmac_f32_e32 v61, v93, v10
	v_fmac_f32_e32 v62, v93, v11
	v_fmac_f32_e32 v63, v93, v14
	v_fmac_f32_e32 v64, v93, v15
	v_fmac_f32_e32 v65, v93, v20
	v_fmac_f32_e32 v66, v93, v21
	v_fmac_f32_e32 v67, v93, v24
	v_fmac_f32_e32 v68, v93, v25
	v_fmac_f32_e32 v70, v93, v29
	v_fmac_f32_e32 v71, v93, v32
	v_fmac_f32_e32 v75, v93, v33
	v_fmac_f32_e32 v46, v92, v30
	v_fmac_f32_e32 v69, v92, v29
	v_fmac_f32_e32 v44, v91, v35
	v_fmac_f32_e32 v45, v91, v30
	v_fmac_f32_e32 v43, v90, v35
	v_fmac_f32_e32 v42, v89, v35
	v_fmac_f32_e32 v41, v88, v35
	ds_read2st64_b32 v[34:35], v40 offset0:192 offset1:196
	v_fmac_f32_e32 v47, v92, v31
	v_fmac_f32_e32 v48, v92, v26
	v_fmac_f32_e32 v49, v92, v27
	v_fmac_f32_e32 v50, v92, v22
	v_fmac_f32_e32 v51, v92, v23
	v_fmac_f32_e32 v52, v92, v18
	v_fmac_f32_e32 v53, v92, v19
	v_fmac_f32_e32 v54, v92, v16
	v_fmac_f32_e32 v55, v92, v17
	v_fmac_f32_e32 v56, v92, v12
	v_fmac_f32_e32 v57, v92, v13
	v_fmac_f32_e32 v58, v92, v8
	v_fmac_f32_e32 v59, v92, v9
	v_fmac_f32_e32 v60, v92, v10
	v_fmac_f32_e32 v61, v92, v11
	v_fmac_f32_e32 v62, v92, v14
	v_fmac_f32_e32 v63, v92, v15
	v_fmac_f32_e32 v64, v92, v20
	v_fmac_f32_e32 v65, v92, v21
	v_fmac_f32_e32 v66, v92, v24
	v_fmac_f32_e32 v67, v92, v25
	v_fmac_f32_e32 v68, v92, v28
	v_fmac_f32_e32 v70, v92, v32
	v_fmac_f32_e32 v71, v92, v33
	s_waitcnt lgkmcnt(2)
	v_fmac_f32_e32 v75, v92, v36
	v_fmac_f32_e32 v46, v91, v31
	v_fmac_f32_e32 v69, v91, v32
	v_fmac_f32_e32 v44, v90, v30
	v_fmac_f32_e32 v45, v90, v31
	v_fmac_f32_e32 v43, v89, v30
	v_fmac_f32_e32 v42, v88, v30
	v_fmac_f32_e32 v41, v87, v30
	v_fmac_f32_e32 v47, v91, v26
	v_fmac_f32_e32 v48, v91, v27
	v_fmac_f32_e32 v49, v91, v22
	v_fmac_f32_e32 v50, v91, v23
	v_fmac_f32_e32 v51, v91, v18
	v_fmac_f32_e32 v52, v91, v19
	v_fmac_f32_e32 v53, v91, v16
	v_fmac_f32_e32 v54, v91, v17
	v_fmac_f32_e32 v55, v91, v12
	v_fmac_f32_e32 v56, v91, v13
	v_fmac_f32_e32 v57, v91, v8
	v_fmac_f32_e32 v58, v91, v9
	v_fmac_f32_e32 v59, v91, v10
	v_fmac_f32_e32 v60, v91, v11
	v_fmac_f32_e32 v61, v91, v14
	v_fmac_f32_e32 v62, v91, v15
	v_fmac_f32_e32 v63, v91, v20
	v_fmac_f32_e32 v64, v91, v21
	v_fmac_f32_e32 v65, v91, v24
	v_fmac_f32_e32 v66, v91, v25
	v_fmac_f32_e32 v67, v91, v28
	v_fmac_f32_e32 v68, v91, v29
	v_fmac_f32_e32 v70, v91, v33
	v_fmac_f32_e32 v71, v91, v36
	v_fmac_f32_e32 v75, v91, v37
	v_fmac_f32_e32 v46, v90, v26
	v_fmac_f32_e32 v69, v90, v33
	v_fmac_f32_e32 v44, v89, v31
	v_fmac_f32_e32 v45, v89, v26
	v_fmac_f32_e32 v43, v88, v31
	v_fmac_f32_e32 v42, v87, v31
	v_fmac_f32_e32 v41, v86, v31
	ds_read2st64_b32 v[30:31], v40 offset0:200 offset1:204
	v_fmac_f32_e32 v47, v90, v27
	v_fmac_f32_e32 v48, v90, v22
	v_fmac_f32_e32 v49, v90, v23
	v_fmac_f32_e32 v50, v90, v18
	v_fmac_f32_e32 v51, v90, v19
	v_fmac_f32_e32 v52, v90, v16
	v_fmac_f32_e32 v53, v90, v17
	v_fmac_f32_e32 v54, v90, v12
	v_fmac_f32_e32 v55, v90, v13
	v_fmac_f32_e32 v56, v90, v8
	v_fmac_f32_e32 v57, v90, v9
	v_fmac_f32_e32 v58, v90, v10
	v_fmac_f32_e32 v59, v90, v11
	v_fmac_f32_e32 v60, v90, v14
	v_fmac_f32_e32 v61, v90, v15
	v_fmac_f32_e32 v62, v90, v20
	v_fmac_f32_e32 v63, v90, v21
	v_fmac_f32_e32 v64, v90, v24
	v_fmac_f32_e32 v65, v90, v25
	v_fmac_f32_e32 v66, v90, v28
	v_fmac_f32_e32 v67, v90, v29
	v_fmac_f32_e32 v68, v90, v32
	v_fmac_f32_e32 v70, v90, v36
	v_fmac_f32_e32 v71, v90, v37
	s_waitcnt lgkmcnt(2)
	v_fmac_f32_e32 v75, v90, v38
	v_fmac_f32_e32 v46, v89, v27
	v_fmac_f32_e32 v69, v89, v36
	v_fmac_f32_e32 v44, v88, v26
	v_fmac_f32_e32 v45, v88, v27
	v_fmac_f32_e32 v43, v87, v26
	v_fmac_f32_e32 v42, v86, v26
	v_fmac_f32_e32 v41, v85, v26
	v_fmac_f32_e32 v47, v89, v22
	v_fmac_f32_e32 v48, v89, v23
	v_fmac_f32_e32 v49, v89, v18
	v_fmac_f32_e32 v50, v89, v19
	v_fmac_f32_e32 v51, v89, v16
	v_fmac_f32_e32 v52, v89, v17
	v_fmac_f32_e32 v53, v89, v12
	v_fmac_f32_e32 v54, v89, v13
	v_fmac_f32_e32 v55, v89, v8
	v_fmac_f32_e32 v56, v89, v9
	v_fmac_f32_e32 v57, v89, v10
	v_fmac_f32_e32 v58, v89, v11
	v_fmac_f32_e32 v59, v89, v14
	v_fmac_f32_e32 v60, v89, v15
	v_fmac_f32_e32 v61, v89, v20
	v_fmac_f32_e32 v62, v89, v21
	v_fmac_f32_e32 v63, v89, v24
	v_fmac_f32_e32 v64, v89, v25
	v_fmac_f32_e32 v65, v89, v28
	v_fmac_f32_e32 v66, v89, v29
	v_fmac_f32_e32 v67, v89, v32
	v_fmac_f32_e32 v68, v89, v33
	v_fmac_f32_e32 v70, v89, v37
	v_fmac_f32_e32 v71, v89, v38
	v_fmac_f32_e32 v75, v89, v39
	v_fmac_f32_e32 v46, v88, v22
	v_fmac_f32_e32 v69, v88, v37
	v_fmac_f32_e32 v44, v87, v27
	v_fmac_f32_e32 v45, v87, v22
	v_fmac_f32_e32 v43, v86, v27
	v_fmac_f32_e32 v42, v85, v27
	v_fmac_f32_e32 v41, v84, v27
	ds_read2st64_b32 v[26:27], v40 offset0:208 offset1:212
	v_fmac_f32_e32 v47, v88, v23
	v_fmac_f32_e32 v48, v88, v18
	v_fmac_f32_e32 v49, v88, v19
	v_fmac_f32_e32 v50, v88, v16
	v_fmac_f32_e32 v51, v88, v17
	v_fmac_f32_e32 v52, v88, v12
	v_fmac_f32_e32 v53, v88, v13
	v_fmac_f32_e32 v54, v88, v8
	v_fmac_f32_e32 v55, v88, v9
	v_fmac_f32_e32 v56, v88, v10
	v_fmac_f32_e32 v57, v88, v11
	v_fmac_f32_e32 v58, v88, v14
	v_fmac_f32_e32 v59, v88, v15
	v_fmac_f32_e32 v60, v88, v20
	v_fmac_f32_e32 v61, v88, v21
	v_fmac_f32_e32 v62, v88, v24
	v_fmac_f32_e32 v63, v88, v25
	v_fmac_f32_e32 v64, v88, v28
	v_fmac_f32_e32 v65, v88, v29
	v_fmac_f32_e32 v66, v88, v32
	v_fmac_f32_e32 v67, v88, v33
	v_fmac_f32_e32 v68, v88, v36
	v_fmac_f32_e32 v70, v88, v38
	v_fmac_f32_e32 v71, v88, v39
	s_waitcnt lgkmcnt(2)
	v_fmac_f32_e32 v75, v88, v34
	v_fmac_f32_e32 v46, v87, v23
	v_fmac_f32_e32 v69, v87, v38
	v_fmac_f32_e32 v44, v86, v22
	v_fmac_f32_e32 v45, v86, v23
	v_fmac_f32_e32 v43, v85, v22
	v_fmac_f32_e32 v42, v84, v22
	v_fmac_f32_e32 v41, v83, v22
	v_fmac_f32_e32 v47, v87, v18
	v_fmac_f32_e32 v48, v87, v19
	v_fmac_f32_e32 v49, v87, v16
	v_fmac_f32_e32 v50, v87, v17
	v_fmac_f32_e32 v51, v87, v12
	v_fmac_f32_e32 v52, v87, v13
	v_fmac_f32_e32 v53, v87, v8
	v_fmac_f32_e32 v54, v87, v9
	v_fmac_f32_e32 v55, v87, v10
	v_fmac_f32_e32 v56, v87, v11
	v_fmac_f32_e32 v57, v87, v14
	v_fmac_f32_e32 v58, v87, v15
	v_fmac_f32_e32 v59, v87, v20
	v_fmac_f32_e32 v60, v87, v21
	v_fmac_f32_e32 v61, v87, v24
	v_fmac_f32_e32 v62, v87, v25
	v_fmac_f32_e32 v63, v87, v28
	v_fmac_f32_e32 v64, v87, v29
	v_fmac_f32_e32 v65, v87, v32
	v_fmac_f32_e32 v66, v87, v33
	v_fmac_f32_e32 v67, v87, v36
	v_fmac_f32_e32 v68, v87, v37
	v_fmac_f32_e32 v70, v87, v39
	v_fmac_f32_e32 v71, v87, v34
	v_fmac_f32_e32 v75, v87, v35
	v_fmac_f32_e32 v46, v86, v18
	v_fmac_f32_e32 v69, v86, v39
	v_fmac_f32_e32 v44, v85, v23
	v_fmac_f32_e32 v45, v85, v18
	v_fmac_f32_e32 v43, v84, v23
	v_fmac_f32_e32 v42, v83, v23
	v_fmac_f32_e32 v41, v82, v23
	ds_read2st64_b32 v[22:23], v40 offset0:216 offset1:220
	v_fmac_f32_e32 v47, v86, v19
	v_fmac_f32_e32 v48, v86, v16
	v_fmac_f32_e32 v49, v86, v17
	v_fmac_f32_e32 v50, v86, v12
	v_fmac_f32_e32 v51, v86, v13
	v_fmac_f32_e32 v52, v86, v8
	v_fmac_f32_e32 v53, v86, v9
	v_fmac_f32_e32 v54, v86, v10
	v_fmac_f32_e32 v55, v86, v11
	v_fmac_f32_e32 v56, v86, v14
	v_fmac_f32_e32 v57, v86, v15
	v_fmac_f32_e32 v58, v86, v20
	v_fmac_f32_e32 v59, v86, v21
	v_fmac_f32_e32 v60, v86, v24
	v_fmac_f32_e32 v61, v86, v25
	v_fmac_f32_e32 v62, v86, v28
	v_fmac_f32_e32 v63, v86, v29
	v_fmac_f32_e32 v64, v86, v32
	v_fmac_f32_e32 v65, v86, v33
	v_fmac_f32_e32 v66, v86, v36
	v_fmac_f32_e32 v67, v86, v37
	v_fmac_f32_e32 v68, v86, v38
	v_fmac_f32_e32 v70, v86, v34
	v_fmac_f32_e32 v71, v86, v35
	s_waitcnt lgkmcnt(2)
	v_fmac_f32_e32 v75, v86, v30
	v_fmac_f32_e32 v46, v85, v19
	v_fmac_f32_e32 v69, v85, v34
	v_fmac_f32_e32 v44, v84, v18
	v_fmac_f32_e32 v45, v84, v19
	v_fmac_f32_e32 v43, v83, v18
	v_fmac_f32_e32 v42, v82, v18
	v_fmac_f32_e32 v41, v81, v18
	v_fmac_f32_e32 v47, v85, v16
	v_fmac_f32_e32 v48, v85, v17
	v_fmac_f32_e32 v49, v85, v12
	v_fmac_f32_e32 v50, v85, v13
	v_fmac_f32_e32 v51, v85, v8
	v_fmac_f32_e32 v52, v85, v9
	v_fmac_f32_e32 v53, v85, v10
	v_fmac_f32_e32 v54, v85, v11
	v_fmac_f32_e32 v55, v85, v14
	v_fmac_f32_e32 v56, v85, v15
	v_fmac_f32_e32 v57, v85, v20
	v_fmac_f32_e32 v58, v85, v21
	v_fmac_f32_e32 v59, v85, v24
	v_fmac_f32_e32 v60, v85, v25
	v_fmac_f32_e32 v61, v85, v28
	v_fmac_f32_e32 v62, v85, v29
	v_fmac_f32_e32 v63, v85, v32
	v_fmac_f32_e32 v64, v85, v33
	v_fmac_f32_e32 v65, v85, v36
	v_fmac_f32_e32 v66, v85, v37
	v_fmac_f32_e32 v67, v85, v38
	v_fmac_f32_e32 v68, v85, v39
	v_fmac_f32_e32 v70, v85, v35
	v_fmac_f32_e32 v71, v85, v30
	v_fmac_f32_e32 v75, v85, v31
	v_fmac_f32_e32 v46, v84, v16
	v_fmac_f32_e32 v69, v84, v35
	v_fmac_f32_e32 v44, v83, v19
	v_fmac_f32_e32 v45, v83, v16
	v_fmac_f32_e32 v43, v82, v19
	v_fmac_f32_e32 v42, v81, v19
	v_fmac_f32_e32 v41, v80, v19
	ds_read2st64_b32 v[18:19], v40 offset0:224 offset1:228
	v_fmac_f32_e32 v47, v84, v17
	v_fmac_f32_e32 v48, v84, v12
	v_fmac_f32_e32 v49, v84, v13
	v_fmac_f32_e32 v50, v84, v8
	v_fmac_f32_e32 v51, v84, v9
	v_fmac_f32_e32 v52, v84, v10
	v_fmac_f32_e32 v53, v84, v11
	v_fmac_f32_e32 v54, v84, v14
	v_fmac_f32_e32 v55, v84, v15
	v_fmac_f32_e32 v56, v84, v20
	v_fmac_f32_e32 v57, v84, v21
	v_fmac_f32_e32 v58, v84, v24
	v_fmac_f32_e32 v59, v84, v25
	v_fmac_f32_e32 v60, v84, v28
	v_fmac_f32_e32 v61, v84, v29
	v_fmac_f32_e32 v62, v84, v32
	v_fmac_f32_e32 v63, v84, v33
	v_fmac_f32_e32 v64, v84, v36
	v_fmac_f32_e32 v65, v84, v37
	v_fmac_f32_e32 v66, v84, v38
	v_fmac_f32_e32 v67, v84, v39
	v_fmac_f32_e32 v68, v84, v34
	v_fmac_f32_e32 v70, v84, v30
	v_fmac_f32_e32 v71, v84, v31
	s_waitcnt lgkmcnt(2)
	v_fmac_f32_e32 v75, v84, v26
	v_fmac_f32_e32 v46, v83, v17
	v_fmac_f32_e32 v69, v83, v30
	v_fmac_f32_e32 v44, v82, v16
	v_fmac_f32_e32 v45, v82, v17
	v_fmac_f32_e32 v43, v81, v16
	v_fmac_f32_e32 v42, v80, v16
	v_fmac_f32_e32 v41, v79, v16
	v_fmac_f32_e32 v47, v83, v12
	v_fmac_f32_e32 v48, v83, v13
	v_fmac_f32_e32 v49, v83, v8
	v_fmac_f32_e32 v50, v83, v9
	v_fmac_f32_e32 v51, v83, v10
	v_fmac_f32_e32 v52, v83, v11
	v_fmac_f32_e32 v53, v83, v14
	v_fmac_f32_e32 v54, v83, v15
	v_fmac_f32_e32 v55, v83, v20
	v_fmac_f32_e32 v56, v83, v21
	v_fmac_f32_e32 v57, v83, v24
	v_fmac_f32_e32 v58, v83, v25
	v_fmac_f32_e32 v59, v83, v28
	v_fmac_f32_e32 v60, v83, v29
	v_fmac_f32_e32 v61, v83, v32
	v_fmac_f32_e32 v62, v83, v33
	v_fmac_f32_e32 v63, v83, v36
	v_fmac_f32_e32 v64, v83, v37
	v_fmac_f32_e32 v65, v83, v38
	v_fmac_f32_e32 v66, v83, v39
	v_fmac_f32_e32 v67, v83, v34
	v_fmac_f32_e32 v68, v83, v35
	v_fmac_f32_e32 v70, v83, v31
	v_fmac_f32_e32 v71, v83, v26
	v_fmac_f32_e32 v75, v83, v27
	v_fmac_f32_e32 v46, v82, v12
	v_fmac_f32_e32 v69, v82, v31
	v_fmac_f32_e32 v44, v81, v17
	v_fmac_f32_e32 v45, v81, v12
	v_fmac_f32_e32 v43, v80, v17
	v_fmac_f32_e32 v42, v79, v17
	v_fmac_f32_e32 v41, v78, v17
	ds_read2st64_b32 v[16:17], v40 offset0:232 offset1:236
	v_fmac_f32_e32 v47, v82, v13
	v_fmac_f32_e32 v48, v82, v8
	v_fmac_f32_e32 v49, v82, v9
	v_fmac_f32_e32 v50, v82, v10
	v_fmac_f32_e32 v51, v82, v11
	v_fmac_f32_e32 v52, v82, v14
	v_fmac_f32_e32 v53, v82, v15
	v_fmac_f32_e32 v54, v82, v20
	v_fmac_f32_e32 v55, v82, v21
	v_fmac_f32_e32 v56, v82, v24
	v_fmac_f32_e32 v57, v82, v25
	v_fmac_f32_e32 v58, v82, v28
	v_fmac_f32_e32 v59, v82, v29
	v_fmac_f32_e32 v60, v82, v32
	v_fmac_f32_e32 v61, v82, v33
	v_fmac_f32_e32 v62, v82, v36
	v_fmac_f32_e32 v63, v82, v37
	v_fmac_f32_e32 v64, v82, v38
	v_fmac_f32_e32 v65, v82, v39
	v_fmac_f32_e32 v66, v82, v34
	v_fmac_f32_e32 v67, v82, v35
	v_fmac_f32_e32 v68, v82, v30
	v_fmac_f32_e32 v70, v82, v26
	v_fmac_f32_e32 v71, v82, v27
	s_waitcnt lgkmcnt(2)
	v_fmac_f32_e32 v75, v82, v22
	v_fmac_f32_e32 v46, v81, v13
	v_fmac_f32_e32 v69, v81, v26
	v_fmac_f32_e32 v44, v80, v12
	v_fmac_f32_e32 v45, v80, v13
	v_fmac_f32_e32 v43, v79, v12
	v_fmac_f32_e32 v42, v78, v12
	v_fmac_f32_e32 v41, v77, v12
	v_fmac_f32_e32 v47, v81, v8
	v_fmac_f32_e32 v48, v81, v9
	v_fmac_f32_e32 v49, v81, v10
	v_fmac_f32_e32 v50, v81, v11
	v_fmac_f32_e32 v51, v81, v14
	v_fmac_f32_e32 v52, v81, v15
	v_fmac_f32_e32 v53, v81, v20
	v_fmac_f32_e32 v54, v81, v21
	v_fmac_f32_e32 v55, v81, v24
	v_fmac_f32_e32 v56, v81, v25
	v_fmac_f32_e32 v57, v81, v28
	v_fmac_f32_e32 v58, v81, v29
	v_fmac_f32_e32 v59, v81, v32
	v_fmac_f32_e32 v60, v81, v33
	v_fmac_f32_e32 v61, v81, v36
	v_fmac_f32_e32 v62, v81, v37
	v_fmac_f32_e32 v63, v81, v38
	v_fmac_f32_e32 v64, v81, v39
	v_fmac_f32_e32 v65, v81, v34
	v_fmac_f32_e32 v66, v81, v35
	v_fmac_f32_e32 v67, v81, v30
	v_fmac_f32_e32 v68, v81, v31
	v_fmac_f32_e32 v70, v81, v27
	v_fmac_f32_e32 v71, v81, v22
	v_fmac_f32_e32 v75, v81, v23
	v_fmac_f32_e32 v46, v80, v8
	v_fmac_f32_e32 v69, v80, v27
	v_fmac_f32_e32 v44, v79, v13
	v_fmac_f32_e32 v45, v79, v8
	v_fmac_f32_e32 v43, v78, v13
	v_fmac_f32_e32 v42, v77, v13
	v_fmac_f32_e32 v41, v76, v13
	ds_read2st64_b32 v[12:13], v40 offset0:240 offset1:244
	v_fmac_f32_e32 v47, v80, v9
	v_fmac_f32_e32 v48, v80, v10
	v_fmac_f32_e32 v49, v80, v11
	v_fmac_f32_e32 v50, v80, v14
	v_fmac_f32_e32 v51, v80, v15
	v_fmac_f32_e32 v52, v80, v20
	v_fmac_f32_e32 v53, v80, v21
	v_fmac_f32_e32 v54, v80, v24
	v_fmac_f32_e32 v55, v80, v25
	v_fmac_f32_e32 v56, v80, v28
	v_fmac_f32_e32 v57, v80, v29
	v_fmac_f32_e32 v58, v80, v32
	v_fmac_f32_e32 v59, v80, v33
	v_fmac_f32_e32 v60, v80, v36
	v_fmac_f32_e32 v61, v80, v37
	v_fmac_f32_e32 v62, v80, v38
	v_fmac_f32_e32 v63, v80, v39
	v_fmac_f32_e32 v64, v80, v34
	v_fmac_f32_e32 v65, v80, v35
	v_fmac_f32_e32 v66, v80, v30
	v_fmac_f32_e32 v67, v80, v31
	v_fmac_f32_e32 v68, v80, v26
	v_fmac_f32_e32 v70, v80, v22
	v_fmac_f32_e32 v71, v80, v23
	s_waitcnt lgkmcnt(2)
	v_fmac_f32_e32 v75, v80, v18
	v_fmac_f32_e32 v46, v79, v9
	v_fmac_f32_e32 v69, v79, v22
	v_fmac_f32_e32 v45, v78, v9
	v_fmac_f32_e32 v47, v79, v10
	v_fmac_f32_e32 v48, v79, v11
	v_fmac_f32_e32 v49, v79, v14
	v_fmac_f32_e32 v50, v79, v15
	v_fmac_f32_e32 v51, v79, v20
	v_fmac_f32_e32 v52, v79, v21
	v_fmac_f32_e32 v53, v79, v24
	v_fmac_f32_e32 v54, v79, v25
	v_fmac_f32_e32 v55, v79, v28
	v_fmac_f32_e32 v56, v79, v29
	v_fmac_f32_e32 v57, v79, v32
	v_fmac_f32_e32 v58, v79, v33
	v_fmac_f32_e32 v59, v79, v36
	v_fmac_f32_e32 v60, v79, v37
	v_fmac_f32_e32 v61, v79, v38
	v_fmac_f32_e32 v62, v79, v39
	v_fmac_f32_e32 v63, v79, v34
	v_fmac_f32_e32 v64, v79, v35
	v_fmac_f32_e32 v65, v79, v30
	v_fmac_f32_e32 v66, v79, v31
	v_fmac_f32_e32 v67, v79, v26
	v_fmac_f32_e32 v68, v79, v27
	v_fmac_f32_e32 v70, v79, v23
	v_fmac_f32_e32 v71, v79, v18
	v_fmac_f32_e32 v75, v79, v19
	v_fmac_f32_e32 v46, v78, v10
	v_fmac_f32_e32 v69, v78, v23
	v_fmac_f32_e32 v45, v77, v10
	v_fmac_f32_e32 v44, v78, v8
	v_fmac_f32_e32 v47, v78, v11
	v_fmac_f32_e32 v48, v78, v14
	v_fmac_f32_e32 v49, v78, v15
	v_fmac_f32_e32 v50, v78, v20
	v_fmac_f32_e32 v51, v78, v21
	v_fmac_f32_e32 v52, v78, v24
	v_fmac_f32_e32 v53, v78, v25
	v_fmac_f32_e32 v54, v78, v28
	v_fmac_f32_e32 v55, v78, v29
	v_fmac_f32_e32 v56, v78, v32
	v_fmac_f32_e32 v57, v78, v33
	v_fmac_f32_e32 v58, v78, v36
	v_fmac_f32_e32 v59, v78, v37
	v_fmac_f32_e32 v60, v78, v38
	v_fmac_f32_e32 v61, v78, v39
	v_fmac_f32_e32 v62, v78, v34
	v_fmac_f32_e32 v63, v78, v35
	v_fmac_f32_e32 v64, v78, v30
	v_fmac_f32_e32 v65, v78, v31
	v_fmac_f32_e32 v66, v78, v26
	v_fmac_f32_e32 v67, v78, v27
	v_fmac_f32_e32 v68, v78, v22
	v_fmac_f32_e32 v70, v78, v18
	v_fmac_f32_e32 v71, v78, v19
	s_waitcnt lgkmcnt(1)
	v_fmac_f32_e32 v75, v78, v16
	v_fmac_f32_e32 v43, v77, v8
	v_fmac_f32_e32 v46, v77, v11
	v_fmac_f32_e32 v69, v77, v18
	v_fmac_f32_e32 v42, v76, v8
	v_fmac_f32_e32 v45, v76, v11
	v_fmac_f32_e32 v41, v74, v8
	v_and_b32_e32 v8, 0xffffffcf, v122
	v_fmac_f32_e32 v44, v77, v9
	v_fmac_f32_e32 v47, v77, v14
	v_fmac_f32_e32 v48, v77, v15
	v_fmac_f32_e32 v49, v77, v20
	v_fmac_f32_e32 v50, v77, v21
	v_fmac_f32_e32 v51, v77, v24
	v_fmac_f32_e32 v52, v77, v25
	v_fmac_f32_e32 v53, v77, v28
	v_fmac_f32_e32 v54, v77, v29
	v_fmac_f32_e32 v55, v77, v32
	v_fmac_f32_e32 v56, v77, v33
	v_fmac_f32_e32 v57, v77, v36
	v_fmac_f32_e32 v58, v77, v37
	v_fmac_f32_e32 v59, v77, v38
	v_fmac_f32_e32 v60, v77, v39
	v_fmac_f32_e32 v61, v77, v34
	v_fmac_f32_e32 v62, v77, v35
	v_fmac_f32_e32 v63, v77, v30
	v_fmac_f32_e32 v64, v77, v31
	v_fmac_f32_e32 v65, v77, v26
	v_fmac_f32_e32 v66, v77, v27
	v_fmac_f32_e32 v67, v77, v22
	v_fmac_f32_e32 v68, v77, v23
	v_fmac_f32_e32 v70, v77, v19
	v_fmac_f32_e32 v71, v77, v16
	v_fmac_f32_e32 v75, v77, v17
	v_fmac_f32_e32 v43, v76, v9
	v_fmac_f32_e32 v46, v76, v14
	v_fmac_f32_e32 v69, v76, v19
	v_fmac_f32_e32 v42, v74, v9
	v_fmac_f32_e32 v45, v74, v14
	v_ashrrev_i32_e32 v9, 31, v8
	v_or_b32_e32 v14, 16, v8
	v_fmac_f32_e32 v44, v76, v10
	v_fmac_f32_e32 v47, v76, v15
	v_fmac_f32_e32 v48, v76, v20
	v_fmac_f32_e32 v49, v76, v21
	v_fmac_f32_e32 v50, v76, v24
	v_fmac_f32_e32 v51, v76, v25
	v_fmac_f32_e32 v52, v76, v28
	v_fmac_f32_e32 v53, v76, v29
	v_fmac_f32_e32 v54, v76, v32
	v_fmac_f32_e32 v55, v76, v33
	v_fmac_f32_e32 v56, v76, v36
	v_fmac_f32_e32 v57, v76, v37
	v_fmac_f32_e32 v58, v76, v38
	v_fmac_f32_e32 v59, v76, v39
	v_fmac_f32_e32 v60, v76, v34
	v_fmac_f32_e32 v61, v76, v35
	v_fmac_f32_e32 v62, v76, v30
	v_fmac_f32_e32 v63, v76, v31
	v_fmac_f32_e32 v64, v76, v26
	v_fmac_f32_e32 v65, v76, v27
	v_fmac_f32_e32 v66, v76, v22
	v_fmac_f32_e32 v67, v76, v23
	v_fmac_f32_e32 v68, v76, v18
	v_fmac_f32_e32 v70, v76, v16
	v_fmac_f32_e32 v71, v76, v17
	s_waitcnt lgkmcnt(0)
	v_fmac_f32_e32 v75, v76, v12
	v_fmac_f32_e32 v46, v74, v15
	v_fmac_f32_e32 v69, v74, v16
	v_and_b32_e32 v200, 48, v123
	v_lshlrev_b64 v[106:107], 9, v[8:9]
	v_ashrrev_i32_e32 v15, 31, v14
	v_or_b32_e32 v8, 32, v8
	v_or_b32_e32 v16, 48, v122
	v_fmac_f32_e32 v43, v74, v10
	v_fmac_f32_e32 v44, v74, v11
	v_fmac_f32_e32 v47, v74, v20
	v_fmac_f32_e32 v48, v74, v21
	v_fmac_f32_e32 v49, v74, v24
	v_fmac_f32_e32 v50, v74, v25
	v_fmac_f32_e32 v51, v74, v28
	v_fmac_f32_e32 v52, v74, v29
	v_fmac_f32_e32 v53, v74, v32
	v_fmac_f32_e32 v54, v74, v33
	v_fmac_f32_e32 v55, v74, v36
	v_fmac_f32_e32 v56, v74, v37
	v_fmac_f32_e32 v57, v74, v38
	v_fmac_f32_e32 v58, v74, v39
	v_fmac_f32_e32 v59, v74, v34
	v_fmac_f32_e32 v60, v74, v35
	v_fmac_f32_e32 v61, v74, v30
	v_fmac_f32_e32 v62, v74, v31
	v_fmac_f32_e32 v63, v74, v26
	v_fmac_f32_e32 v64, v74, v27
	v_fmac_f32_e32 v65, v74, v22
	v_fmac_f32_e32 v66, v74, v23
	v_fmac_f32_e32 v67, v74, v18
	v_fmac_f32_e32 v68, v74, v19
	v_fmac_f32_e32 v70, v74, v17
	v_fmac_f32_e32 v71, v74, v12
	v_fmac_f32_e32 v75, v74, v13
	s_waitcnt lgkmcnt(0)
	s_barrier
	ds_write2st64_b32 v40, v41, v42 offset1:4
	ds_write2st64_b32 v40, v43, v44 offset0:8 offset1:12
	ds_write2st64_b32 v40, v45, v46 offset0:16 offset1:20
	ds_write2st64_b32 v40, v47, v48 offset0:24 offset1:28
	ds_write2st64_b32 v40, v49, v50 offset0:32 offset1:36
	ds_write2st64_b32 v40, v51, v52 offset0:40 offset1:44
	ds_write2st64_b32 v40, v53, v54 offset0:48 offset1:52
	ds_write2st64_b32 v40, v55, v56 offset0:56 offset1:60
	ds_write2st64_b32 v40, v57, v58 offset0:64 offset1:68
	ds_write2st64_b32 v40, v59, v60 offset0:72 offset1:76
	ds_write2st64_b32 v40, v61, v62 offset0:80 offset1:84
	ds_write2st64_b32 v40, v63, v64 offset0:88 offset1:92
	ds_write2st64_b32 v40, v65, v66 offset0:96 offset1:100
	ds_write2st64_b32 v40, v67, v68 offset0:104 offset1:108
	ds_write2st64_b32 v40, v69, v70 offset0:112 offset1:116
	ds_write2st64_b32 v40, v71, v75 offset0:120 offset1:124
	v_lshl_add_u64 v[10:11], s[86:87], 0, v[200:201]
	v_lshlrev_b64 v[110:111], 9, v[14:15]
	v_ashrrev_i32_e32 v9, 31, v8
	v_ashrrev_i32_e32 v17, 31, v16
	s_waitcnt lgkmcnt(0)
	s_barrier
	v_lshl_add_u64 v[12:13], v[10:11], 0, v[106:107]
	v_lshl_add_u64 v[14:15], v[10:11], 0, v[110:111]
	v_lshlrev_b64 v[112:113], 9, v[8:9]
	v_lshlrev_b64 v[108:109], 9, v[16:17]
	v_lshl_add_u32 v114, v124, 13, v102
	v_lshl_add_u64 v[8:9], v[10:11], 0, v[112:113]
	v_lshl_add_u64 v[10:11], v[10:11], 0, v[108:109]
	global_load_dwordx4 v[56:59], v[12:13], off
	global_load_dwordx4 v[40:43], v[12:13], off offset:64
	global_load_dwordx4 v[60:63], v[14:15], off
	global_load_dwordx4 v[44:47], v[14:15], off offset:64
	global_load_dwordx4 v[64:67], v[8:9], off
	global_load_dwordx4 v[48:51], v[8:9], off offset:64
	global_load_dwordx4 v[68:71], v[10:11], off
	global_load_dwordx4 v[52:55], v[10:11], off offset:64
	global_load_dwordx4 v[24:27], v[12:13], off offset:128
	global_load_dwordx4 v[20:23], v[12:13], off offset:192
	global_load_dwordx4 v[28:31], v[14:15], off offset:128
	s_nop 0
	global_load_dwordx4 v[12:15], v[14:15], off offset:192
	ds_read_b128 v[100:103], v114
	global_load_dwordx4 v[32:35], v[8:9], off offset:128
	global_load_dwordx4 v[16:19], v[8:9], off offset:192
	global_load_dwordx4 v[36:39], v[10:11], off offset:128
	s_nop 0
	global_load_dwordx4 v[8:11], v[10:11], off offset:192
	ds_read_b128 v[96:99], v114 offset:1024
	ds_read_b128 v[92:95], v114 offset:2048
	ds_read_b128 v[88:91], v114 offset:3072
	ds_read_b128 v[84:87], v114 offset:4096
	s_waitcnt lgkmcnt(4)
	v_mov_b32_e32 v72, v101
	v_mov_b32_e32 v73, v102
	v_mov_b32_e32 v74, v100
	v_mov_b32_e32 v75, v103
	v_pk_add_f32 v[72:73], v[72:73], v[74:75]
	s_waitcnt lgkmcnt(3)
	v_mov_b32_e32 v74, v96
	v_add_f32_e32 v118, v72, v73
	v_mov_b32_e32 v72, v97
	v_mov_b32_e32 v73, v98
	v_mov_b32_e32 v75, v99
	v_pk_add_f32 v[72:73], v[72:73], v[74:75]
	s_waitcnt lgkmcnt(2)
	v_mov_b32_e32 v74, v92
	v_add_f32_e32 v119, v72, v73
	v_mov_b32_e32 v72, v93
	v_mov_b32_e32 v73, v94
	v_mov_b32_e32 v75, v95
	v_pk_add_f32 v[72:73], v[72:73], v[74:75]
	ds_read_b128 v[80:83], v114 offset:5120
	ds_read_b128 v[76:79], v114 offset:6144
	v_add_f32_e32 v120, v72, v73
	s_waitcnt lgkmcnt(3)
	v_mov_b32_e32 v72, v89
	v_mov_b32_e32 v73, v90
	v_mov_b32_e32 v74, v88
	v_mov_b32_e32 v75, v91
	v_pk_add_f32 v[72:73], v[72:73], v[74:75]
	s_waitcnt lgkmcnt(2)
	v_mov_b32_e32 v74, v84
	v_add_f32_e32 v121, v72, v73
	v_mov_b32_e32 v72, v85
	v_mov_b32_e32 v73, v86
	v_mov_b32_e32 v75, v87
	v_pk_add_f32 v[72:73], v[72:73], v[74:75]
	s_waitcnt lgkmcnt(1)
	v_mov_b32_e32 v74, v80
	v_add_f32_e32 v126, v72, v73
	v_mov_b32_e32 v72, v81
	v_mov_b32_e32 v73, v82
	v_mov_b32_e32 v75, v83
	v_pk_add_f32 v[72:73], v[72:73], v[74:75]
	s_waitcnt lgkmcnt(0)
	v_mov_b32_e32 v115, v78
	v_add_f32_e32 v127, v72, v73
	ds_read_b128 v[72:75], v114 offset:7168
	v_mov_b32_e32 v114, v77
	v_mov_b32_e32 v116, v76
	v_mov_b32_e32 v117, v79
	v_pk_add_f32 v[114:115], v[114:115], v[116:117]
	s_waitcnt lgkmcnt(0)
	v_mov_b32_e32 v116, v72
	v_add_f32_e32 v128, v114, v115
	v_mov_b32_e32 v114, v73
	v_mov_b32_e32 v115, v74
	v_mov_b32_e32 v117, v75
	v_pk_add_f32 v[114:115], v[114:115], v[116:117]
	v_cmp_lt_i32_e32 vcc, v239, v238
	v_add_f32_e32 v114, v114, v115
	s_mov_b32 s0, 0x358637bd
	v_cndmask_b32_e32 v115, v237, v239, vcc
	v_lshlrev_b32_e32 v125, 2, v115
	ds_bpermute_b32 v116, v125, v119
	ds_bpermute_b32 v130, v125, v126
	ds_bpermute_b32 v115, v125, v118
	ds_bpermute_b32 v117, v125, v120
	ds_bpermute_b32 v131, v125, v127
	ds_bpermute_b32 v129, v125, v121
	ds_bpermute_b32 v132, v125, v128
	v_cmp_lt_i32_e32 vcc, v240, v238
	s_waitcnt lgkmcnt(6)
	v_add_f32_e32 v116, v119, v116
	s_waitcnt lgkmcnt(5)
	v_add_f32_e32 v119, v126, v130
	v_cndmask_b32_e32 v126, v237, v240, vcc
	s_waitcnt lgkmcnt(4)
	v_add_f32_e32 v115, v118, v115
	v_lshlrev_b32_e32 v126, 2, v126
	ds_bpermute_b32 v133, v125, v114
	s_waitcnt lgkmcnt(4)
	v_add_f32_e32 v117, v120, v117
	s_waitcnt lgkmcnt(3)
	v_add_f32_e32 v120, v127, v131
	ds_bpermute_b32 v127, v126, v115
	s_waitcnt lgkmcnt(3)
	v_add_f32_e32 v118, v121, v129
	s_waitcnt lgkmcnt(2)
	v_add_f32_e32 v121, v128, v132
	ds_bpermute_b32 v128, v126, v116
	ds_bpermute_b32 v129, v126, v117
	v_cmp_lt_i32_e32 vcc, v241, v238
	s_waitcnt lgkmcnt(3)
	v_add_f32_e32 v114, v114, v133
	s_waitcnt lgkmcnt(2)
	v_add_f32_e32 v115, v115, v127
	v_cndmask_b32_e32 v127, v237, v241, vcc
	ds_bpermute_b32 v130, v126, v118
	ds_bpermute_b32 v134, v126, v114
	v_lshlrev_b32_e32 v127, 2, v127
	ds_bpermute_b32 v131, v126, v119
	ds_bpermute_b32 v132, v126, v120
	ds_bpermute_b32 v133, v126, v121
	s_waitcnt lgkmcnt(6)
	v_add_f32_e32 v116, v116, v128
	ds_bpermute_b32 v128, v127, v115
	s_waitcnt lgkmcnt(6)
	v_add_f32_e32 v117, v117, v129
	ds_bpermute_b32 v129, v127, v116
	s_waitcnt lgkmcnt(6)
	v_add_f32_e32 v118, v118, v130
	s_waitcnt lgkmcnt(5)
	v_add_f32_e32 v114, v114, v134
	ds_bpermute_b32 v130, v127, v117
	v_cmp_lt_i32_e32 vcc, v242, v238
	s_waitcnt lgkmcnt(5)
	v_add_f32_e32 v119, v119, v131
	s_waitcnt lgkmcnt(4)
	v_add_f32_e32 v120, v120, v132
	s_waitcnt lgkmcnt(3)
	v_add_f32_e32 v121, v121, v133
	ds_bpermute_b32 v131, v127, v118
	ds_bpermute_b32 v135, v127, v114
	s_waitcnt lgkmcnt(4)
	v_add_f32_e32 v115, v115, v128
	v_cndmask_b32_e32 v128, v237, v242, vcc
	ds_bpermute_b32 v132, v127, v119
	ds_bpermute_b32 v133, v127, v120
	ds_bpermute_b32 v134, v127, v121
	v_lshlrev_b32_e32 v128, 2, v128
	s_waitcnt lgkmcnt(6)
	v_add_f32_e32 v116, v116, v129
	ds_bpermute_b32 v129, v128, v115
	s_waitcnt lgkmcnt(6)
	v_add_f32_e32 v117, v117, v130
	ds_bpermute_b32 v130, v128, v116
	s_waitcnt lgkmcnt(6)
	v_add_f32_e32 v118, v118, v131
	s_waitcnt lgkmcnt(5)
	v_add_f32_e32 v114, v114, v135
	ds_bpermute_b32 v131, v128, v117
	s_waitcnt lgkmcnt(5)
	v_add_f32_e32 v119, v119, v132
	s_waitcnt lgkmcnt(4)
	v_add_f32_e32 v120, v120, v133
	s_waitcnt lgkmcnt(3)
	v_add_f32_e32 v121, v121, v134
	ds_bpermute_b32 v132, v128, v118
	ds_bpermute_b32 v136, v128, v114
	v_cmp_lt_i32_e32 vcc, v243, v238
	ds_bpermute_b32 v133, v128, v119
	ds_bpermute_b32 v134, v128, v120
	ds_bpermute_b32 v135, v128, v121
	s_waitcnt lgkmcnt(7)
	v_add_f32_e32 v115, v115, v129
	v_cndmask_b32_e32 v129, v237, v243, vcc
	v_lshlrev_b32_e32 v129, 2, v129
	s_waitcnt lgkmcnt(6)
	v_add_f32_e32 v116, v116, v130
	ds_bpermute_b32 v130, v129, v115
	s_waitcnt lgkmcnt(6)
	v_add_f32_e32 v117, v117, v131
	s_waitcnt lgkmcnt(5)
	v_add_f32_e32 v118, v118, v132
	s_waitcnt lgkmcnt(4)
	v_add_f32_e32 v114, v114, v136
	ds_bpermute_b32 v131, v129, v116
	ds_bpermute_b32 v132, v129, v117
	s_waitcnt lgkmcnt(5)
	v_add_f32_e32 v119, v119, v133
	s_waitcnt lgkmcnt(4)
	v_add_f32_e32 v120, v120, v134
	s_waitcnt lgkmcnt(3)
	v_add_f32_e32 v121, v121, v135
	ds_bpermute_b32 v133, v129, v118
	ds_bpermute_b32 v137, v129, v114
	ds_bpermute_b32 v135, v129, v120
	ds_bpermute_b32 v136, v129, v121
	v_cmp_lt_i32_e32 vcc, v244, v238
	s_waitcnt lgkmcnt(6)
	v_add_f32_e32 v115, v115, v130
	ds_bpermute_b32 v134, v129, v119
	v_cndmask_b32_e32 v130, v237, v244, vcc
	v_lshlrev_b32_e32 v130, 2, v130
	s_waitcnt lgkmcnt(6)
	v_add_f32_e32 v116, v116, v131
	s_waitcnt lgkmcnt(5)
	v_add_f32_e32 v117, v117, v132
	ds_bpermute_b32 v131, v130, v115
	s_waitcnt lgkmcnt(5)
	v_add_f32_e32 v118, v118, v133
	s_waitcnt lgkmcnt(4)
	v_add_f32_e32 v114, v114, v137
	ds_bpermute_b32 v132, v130, v116
	ds_bpermute_b32 v133, v130, v117
	s_waitcnt lgkmcnt(5)
	v_add_f32_e32 v120, v120, v135
	s_waitcnt lgkmcnt(4)
	v_add_f32_e32 v121, v121, v136
	ds_bpermute_b32 v138, v130, v114
	ds_bpermute_b32 v136, v130, v120
	ds_bpermute_b32 v137, v130, v121
	s_waitcnt lgkmcnt(6)
	v_add_f32_e32 v119, v119, v134
	s_waitcnt lgkmcnt(5)
	v_add_f32_e32 v115, v115, v131
	ds_bpermute_b32 v134, v130, v118
	ds_bpermute_b32 v135, v130, v119
	s_waitcnt lgkmcnt(6)
	v_add_f32_e32 v131, v116, v132
	s_waitcnt lgkmcnt(5)
	v_add_f32_e32 v139, v117, v133
	v_fmamk_f32 v133, v115, 0xbb800000, v101
	v_fmamk_f32 v132, v115, 0xbb800000, v100
	v_fmamk_f32 v103, v115, 0xbb800000, v103
	v_fmac_f32_e32 v102, 0xbb800000, v115
	s_waitcnt lgkmcnt(4)
	v_add_f32_e32 v144, v114, v138
	v_pk_mul_f32 v[100:101], v[102:103], v[102:103]
	v_pk_mul_f32 v[114:115], v[132:133], v[132:133]
	s_waitcnt lgkmcnt(3)
	v_add_f32_e32 v142, v120, v136
	s_waitcnt lgkmcnt(2)
	v_add_f32_e32 v143, v121, v137
	v_pk_mov_b32 v[116:117], v[114:115], v[100:101] op_sel:[1,0]
	v_mov_b32_e32 v115, v101
	v_fmamk_f32 v121, v131, 0xbb800000, v97
	v_fmamk_f32 v120, v131, 0xbb800000, v96
	v_fmamk_f32 v99, v131, 0xbb800000, v99
	v_fmac_f32_e32 v98, 0xbb800000, v131
	v_pk_add_f32 v[100:101], v[116:117], v[114:115]
	v_pk_mul_f32 v[96:97], v[98:99], v[98:99]
	v_pk_mul_f32 v[114:115], v[120:121], v[120:121]
	s_waitcnt lgkmcnt(1)
	v_add_f32_e32 v140, v118, v134
	v_pk_mov_b32 v[116:117], v[114:115], v[96:97] op_sel:[1,0]
	v_mov_b32_e32 v115, v97
	s_waitcnt lgkmcnt(0)
	v_add_f32_e32 v141, v119, v135
	v_pk_add_f32 v[118:119], v[116:117], v[114:115]
	v_fmamk_f32 v117, v139, 0xbb800000, v93
	v_fmamk_f32 v116, v139, 0xbb800000, v92
	v_fmamk_f32 v95, v139, 0xbb800000, v95
	v_fmac_f32_e32 v94, 0xbb800000, v139
	v_pk_mul_f32 v[92:93], v[94:95], v[94:95]
	v_pk_mul_f32 v[96:97], v[116:117], v[116:117]
	v_fmamk_f32 v91, v140, 0xbb800000, v91
	v_pk_mov_b32 v[114:115], v[96:97], v[92:93] op_sel:[1,0]
	v_mov_b32_e32 v97, v93
	v_pk_add_f32 v[134:135], v[114:115], v[96:97]
	v_fmamk_f32 v97, v140, 0xbb800000, v89
	v_fmamk_f32 v96, v140, 0xbb800000, v88
	v_fmac_f32_e32 v90, 0xbb800000, v140
	v_pk_mul_f32 v[88:89], v[90:91], v[90:91]
	v_pk_mul_f32 v[92:93], v[96:97], v[96:97]
	v_fmamk_f32 v87, v141, 0xbb800000, v87
	v_pk_mov_b32 v[114:115], v[92:93], v[88:89] op_sel:[1,0]
	v_mov_b32_e32 v93, v89
	v_fmamk_f32 v89, v141, 0xbb800000, v85
	v_fmamk_f32 v88, v141, 0xbb800000, v84
	v_fmac_f32_e32 v86, 0xbb800000, v141
	v_pk_add_f32 v[136:137], v[114:115], v[92:93]
	v_pk_mul_f32 v[84:85], v[86:87], v[86:87]
	v_pk_mul_f32 v[92:93], v[88:89], v[88:89]
	v_fmamk_f32 v81, v142, 0xbb800000, v81
	v_pk_mov_b32 v[114:115], v[92:93], v[84:85] op_sel:[1,0]
	v_mov_b32_e32 v93, v85
	v_mov_b32_e32 v84, v118
	v_mov_b32_e32 v85, v100
	v_mov_b32_e32 v100, v119
	v_pk_add_f32 v[84:85], v[84:85], v[100:101]
	v_pk_add_f32 v[114:115], v[114:115], v[92:93]
	ds_bpermute_b32 v93, v125, v85
	ds_bpermute_b32 v92, v125, v84
	v_fmamk_f32 v80, v142, 0xbb800000, v80
	v_fmamk_f32 v83, v142, 0xbb800000, v83
	v_fmac_f32_e32 v82, 0xbb800000, v142
	v_pk_mul_f32 v[100:101], v[82:83], v[82:83]
	s_waitcnt lgkmcnt(0)
	v_pk_add_f32 v[84:85], v[84:85], v[92:93]
	ds_bpermute_b32 v93, v126, v85
	ds_bpermute_b32 v92, v126, v84
	v_pk_mul_f32 v[118:119], v[80:81], v[80:81]
	v_fmamk_f32 v77, v143, 0xbb800000, v77
	v_pk_mov_b32 v[138:139], v[118:119], v[100:101] op_sel:[1,0]
	v_mov_b32_e32 v119, v101
	s_waitcnt lgkmcnt(0)
	v_pk_add_f32 v[84:85], v[84:85], v[92:93]
	ds_bpermute_b32 v93, v127, v85
	ds_bpermute_b32 v92, v127, v84
	v_fmamk_f32 v76, v143, 0xbb800000, v76
	v_fmamk_f32 v79, v143, 0xbb800000, v79
	v_fmac_f32_e32 v78, 0xbb800000, v143
	v_pk_add_f32 v[118:119], v[138:139], v[118:119]
	s_waitcnt lgkmcnt(0)
	v_pk_add_f32 v[84:85], v[84:85], v[92:93]
	ds_bpermute_b32 v93, v128, v85
	ds_bpermute_b32 v92, v128, v84
	v_pk_mul_f32 v[100:101], v[78:79], v[78:79]
	v_pk_mul_f32 v[138:139], v[76:77], v[76:77]
	s_mov_b32 s28, 0x3b800000
	v_pk_mov_b32 v[140:141], v[138:139], v[100:101] op_sel:[1,0]
	s_waitcnt lgkmcnt(0)
	v_pk_add_f32 v[84:85], v[84:85], v[92:93]
	v_mov_b32_e32 v139, v101
	ds_bpermute_b32 v101, v129, v85
	ds_bpermute_b32 v100, v129, v84
	v_fmamk_f32 v73, v144, 0xbb800000, v73
	v_fmamk_f32 v72, v144, 0xbb800000, v72
	v_fmamk_f32 v75, v144, 0xbb800000, v75
	v_fmac_f32_e32 v74, 0xbb800000, v144
	s_waitcnt lgkmcnt(0)
	v_pk_add_f32 v[84:85], v[84:85], v[100:101]
	ds_bpermute_b32 v101, v130, v85
	ds_bpermute_b32 v100, v130, v84
	v_pk_add_f32 v[92:93], v[140:141], v[138:139]
	v_pk_mul_f32 v[138:139], v[74:75], v[74:75]
	v_pk_mul_f32 v[140:141], v[72:73], v[72:73]
	v_and_b32_e32 v105, 15, v122
	s_waitcnt lgkmcnt(0)
	v_pk_add_f32 v[100:101], v[84:85], v[100:101]
	v_mov_b64_e32 v[84:85], s[0:1]
	v_pk_fma_f32 v[144:145], v[100:101], s[28:29], v[84:85] op_sel_hi:[1,0,0]
	s_mov_b32 s1, 0x800000
	v_mul_f32_e32 v100, 0x4b800000, v145
	v_cmp_gt_f32_e32 vcc, s1, v145
	s_movk_i32 s0, 0x1080
	v_pk_mov_b32 v[142:143], v[140:141], v[138:139] op_sel:[1,0]
	v_cndmask_b32_e32 v100, v145, v100, vcc
	v_rsq_f32_e32 v131, v100
	v_mul_lo_u32 v138, v124, s0
	v_mov_b32_e32 v141, v139
	v_pk_add_f32 v[100:101], v[142:143], v[140:141]
	v_mul_f32_e32 v124, 0x45800000, v131
	v_cndmask_b32_e32 v124, v131, v124, vcc
	v_pk_mul_f32 v[132:133], v[132:133], v[124:125] op_sel_hi:[1,0]
	v_add3_u32 v142, s69, v104, v138
	v_pk_fma_f32 v[132:133], v[0:1], v[132:133], v[4:5]
	v_pk_mul_f32 v[102:103], v[102:103], v[124:125] op_sel_hi:[1,0]
	v_mul_f32_e32 v131, 0xbfb8aa3b, v132
	v_exp_f32_e32 v131, v131
	v_mul_f32_e32 v139, 0xbfb8aa3b, v133
	v_exp_f32_e32 v139, v139
	v_pk_fma_f32 v[102:103], v[2:3], v[102:103], v[6:7]
	v_add_f32_e32 v104, 1.0, v131
	v_rcp_f32_e32 v138, v104
	v_add_f32_e32 v104, 1.0, v139
	v_rcp_f32_e32 v139, v104
	v_mul_f32_e32 v104, 0xbfb8aa3b, v102
	v_exp_f32_e32 v104, v104
	v_mul_f32_e32 v124, 0xbfb8aa3b, v103
	v_exp_f32_e32 v124, v124
	v_mov_b32_e32 v140, v136
	v_mov_b32_e32 v141, v134
	v_mov_b32_e32 v134, v137
	v_pk_add_f32 v[134:135], v[140:141], v[134:135]
	v_add_f32_e32 v104, 1.0, v104
	ds_bpermute_b32 v137, v125, v135
	ds_bpermute_b32 v136, v125, v134
	v_pk_mul_f32 v[132:133], v[132:133], v[138:139]
	v_rcp_f32_e32 v138, v104
	v_add_f32_e32 v104, 1.0, v124
	v_rcp_f32_e32 v139, v104
	v_mul_f32_e32 v104, 0x4b800000, v144
	v_cmp_gt_f32_e32 vcc, s1, v144
	s_waitcnt lgkmcnt(0)
	v_pk_add_f32 v[134:135], v[134:135], v[136:137]
	ds_bpermute_b32 v137, v126, v135
	v_cndmask_b32_e32 v104, v144, v104, vcc
	v_rsq_f32_e32 v104, v104
	ds_bpermute_b32 v136, v126, v134
	v_pk_mul_f32 v[102:103], v[102:103], v[138:139]
	v_cvt_pk_bf16_f32 v132, v132, v133
	v_mul_f32_e32 v124, 0x45800000, v104
	v_cndmask_b32_e32 v104, v104, v124, vcc
	v_pk_mul_f32 v[120:121], v[120:121], v[104:105] op_sel_hi:[1,0]
	s_waitcnt lgkmcnt(0)
	v_pk_add_f32 v[134:135], v[134:135], v[136:137]
	v_pk_fma_f32 v[120:121], v[0:1], v[120:121], v[4:5]
	ds_bpermute_b32 v137, v127, v135
	v_mul_f32_e32 v124, 0xbfb8aa3b, v120
	ds_bpermute_b32 v136, v127, v134
	v_exp_f32_e32 v124, v124
	v_mul_f32_e32 v131, 0xbfb8aa3b, v121
	v_exp_f32_e32 v131, v131
	v_cvt_pk_bf16_f32 v133, v102, v103
	v_add_f32_e32 v124, 1.0, v124
	s_waitcnt lgkmcnt(0)
	v_pk_add_f32 v[134:135], v[134:135], v[136:137]
	v_rcp_f32_e32 v140, v124
	v_add_f32_e32 v124, 1.0, v131
	ds_bpermute_b32 v137, v128, v135
	ds_bpermute_b32 v136, v128, v134
	v_rcp_f32_e32 v141, v124
	v_pk_mul_f32 v[98:99], v[98:99], v[104:105] op_sel_hi:[1,0]
	s_ashr_i32 s40, s94, 3
	v_pk_fma_f32 v[98:99], v[2:3], v[98:99], v[6:7]
	v_pk_mul_f32 v[102:103], v[120:121], v[140:141]
	s_waitcnt lgkmcnt(0)
	v_pk_add_f32 v[120:121], v[134:135], v[136:137]
	ds_bpermute_b32 v135, v129, v121
	ds_bpermute_b32 v134, v129, v120
	v_mul_f32_e32 v104, 0xbfb8aa3b, v98
	v_exp_f32_e32 v104, v104
	v_cvt_pk_bf16_f32 v102, v102, v103
	s_lshl_b32 s3, s40, 7
	s_waitcnt lgkmcnt(0)
	v_pk_add_f32 v[120:121], v[120:121], v[134:135]
	ds_bpermute_b32 v135, v130, v121
	ds_bpermute_b32 v134, v130, v120
	v_add_f32_e32 v103, 1.0, v104
	v_mul_f32_e32 v104, 0xbfb8aa3b, v99
	v_exp_f32_e32 v104, v104
	v_readlane_b32 s44, v253, 3
	s_waitcnt lgkmcnt(0)
	v_pk_add_f32 v[120:121], v[120:121], v[134:135]
	v_rcp_f32_e32 v134, v103
	v_pk_fma_f32 v[120:121], v[120:121], s[28:29], v[84:85] op_sel_hi:[1,0,0]
	v_add_f32_e32 v103, 1.0, v104
	v_mul_f32_e32 v124, 0x4b800000, v121
	v_cmp_gt_f32_e32 vcc, s1, v121
	v_rcp_f32_e32 v135, v103
	v_readlane_b32 s52, v253, 11
	v_cndmask_b32_e32 v121, v121, v124, vcc
	v_rsq_f32_e32 v121, v121
	v_pk_mul_f32 v[98:99], v[98:99], v[134:135]
	v_readlane_b32 s53, v253, 12
	s_mul_i32 s38, s40, 0xb0000
	v_mul_f32_e32 v103, 0x45800000, v121
	v_cndmask_b32_e32 v104, v121, v103, vcc
	v_pk_mul_f32 v[116:117], v[116:117], v[104:105] op_sel_hi:[1,0]
	v_pk_mul_f32 v[94:95], v[94:95], v[104:105] op_sel_hi:[1,0]
	v_pk_fma_f32 v[116:117], v[0:1], v[116:117], v[4:5]
	v_pk_fma_f32 v[94:95], v[2:3], v[94:95], v[6:7]
	v_mul_f32_e32 v103, 0xbfb8aa3b, v116
	v_exp_f32_e32 v103, v103
	v_mul_f32_e32 v121, 0xbfb8aa3b, v117
	v_exp_f32_e32 v121, v121
	v_cmp_gt_f32_e32 vcc, s1, v120
	v_add_f32_e32 v103, 1.0, v103
	v_rcp_f32_e32 v134, v103
	v_add_f32_e32 v103, 1.0, v121
	v_rcp_f32_e32 v135, v103
	v_cvt_pk_bf16_f32 v103, v98, v99
	v_add_u32_e32 v121, 0x8000, v142
	ds_write2_b64 v121, v[132:133], v[102:103] offset1:66
	v_mul_f32_e32 v102, 0xbfb8aa3b, v94
	v_exp_f32_e32 v102, v102
	v_mul_f32_e32 v103, 0xbfb8aa3b, v95
	v_exp_f32_e32 v103, v103
	v_pk_mul_f32 v[98:99], v[116:117], v[134:135]
	v_mov_b32_e32 v116, v118
	v_mov_b32_e32 v117, v114
	v_mov_b32_e32 v114, v119
	v_cvt_pk_bf16_f32 v98, v98, v99
	v_add_f32_e32 v99, 1.0, v102
	v_pk_add_f32 v[114:115], v[116:117], v[114:115]
	v_rcp_f32_e32 v102, v99
	v_add_f32_e32 v99, 1.0, v103
	ds_bpermute_b32 v117, v125, v115
	ds_bpermute_b32 v116, v125, v114
	v_rcp_f32_e32 v103, v99
	v_mul_f32_e32 v99, 0x4b800000, v120
	v_cndmask_b32_e32 v99, v120, v99, vcc
	v_rsq_f32_e32 v104, v99
	v_pk_mul_f32 v[94:95], v[94:95], v[102:103]
	s_waitcnt lgkmcnt(0)
	v_pk_add_f32 v[102:103], v[114:115], v[116:117]
	ds_bpermute_b32 v115, v126, v103
	ds_bpermute_b32 v114, v126, v102
	v_cvt_pk_bf16_f32 v99, v94, v95
	v_mul_f32_e32 v94, 0x45800000, v104
	v_cndmask_b32_e32 v94, v104, v94, vcc
	v_pk_mul_f32 v[96:97], v[96:97], v[94:95] op_sel_hi:[1,0]
	s_waitcnt lgkmcnt(0)
	v_pk_add_f32 v[102:103], v[102:103], v[114:115]
	v_pk_fma_f32 v[96:97], v[0:1], v[96:97], v[4:5]
	ds_bpermute_b32 v115, v127, v103
	v_mul_f32_e32 v95, 0xbfb8aa3b, v96
	v_exp_f32_e32 v95, v95
	ds_bpermute_b32 v114, v127, v102
	s_mul_hi_i32 s39, s3, 0x1600
	v_readlane_b32 s45, v253, 4
	v_add_f32_e32 v95, 1.0, v95
	v_rcp_f32_e32 v116, v95
	v_mul_f32_e32 v95, 0xbfb8aa3b, v97
	s_waitcnt lgkmcnt(0)
	v_pk_add_f32 v[102:103], v[102:103], v[114:115]
	v_exp_f32_e32 v95, v95
	ds_bpermute_b32 v115, v128, v103
	ds_bpermute_b32 v114, v128, v102
	v_readlane_b32 s46, v253, 5
	v_add_f32_e32 v95, 1.0, v95
	v_rcp_f32_e32 v117, v95
	v_pk_mul_f32 v[90:91], v[90:91], v[94:95] op_sel_hi:[1,0]
	s_waitcnt lgkmcnt(0)
	v_pk_add_f32 v[94:95], v[102:103], v[114:115]
	ds_bpermute_b32 v103, v129, v95
	ds_bpermute_b32 v102, v129, v94
	v_pk_fma_f32 v[90:91], v[2:3], v[90:91], v[6:7]
	v_pk_mul_f32 v[96:97], v[96:97], v[116:117]
	v_mul_f32_e32 v104, 0xbfb8aa3b, v90
	v_exp_f32_e32 v104, v104
	s_waitcnt lgkmcnt(0)
	v_pk_add_f32 v[94:95], v[94:95], v[102:103]
	ds_bpermute_b32 v103, v130, v95
	ds_bpermute_b32 v102, v130, v94
	v_mul_f32_e32 v114, 0xbfb8aa3b, v91
	v_exp_f32_e32 v115, v114
	v_cvt_pk_bf16_f32 v96, v96, v97
	v_add_f32_e32 v104, 1.0, v104
	s_waitcnt lgkmcnt(0)
	v_pk_add_f32 v[94:95], v[94:95], v[102:103]
	v_rcp_f32_e32 v114, v104
	v_pk_fma_f32 v[94:95], v[94:95], s[28:29], v[84:85] op_sel_hi:[1,0,0]
	v_add_f32_e32 v104, 1.0, v115
	v_mul_f32_e32 v102, 0x4b800000, v95
	v_cmp_gt_f32_e32 vcc, s1, v95
	v_rcp_f32_e32 v115, v104
	v_readlane_b32 s47, v253, 6
	v_cndmask_b32_e32 v95, v95, v102, vcc
	v_rsq_f32_e32 v95, v95
	v_pk_mul_f32 v[90:91], v[90:91], v[114:115]
	v_readlane_b32 s48, v253, 7
	v_readlane_b32 s49, v253, 8
	v_mul_f32_e32 v97, 0x45800000, v95
	v_cndmask_b32_e32 v102, v95, v97, vcc
	v_pk_mul_f32 v[88:89], v[88:89], v[102:103] op_sel_hi:[1,0]
	v_cmp_gt_f32_e32 vcc, s1, v94
	v_pk_fma_f32 v[88:89], v[0:1], v[88:89], v[4:5]
	v_readlane_b32 s50, v253, 9
	v_mul_f32_e32 v95, 0xbfb8aa3b, v88
	v_mul_f32_e32 v97, 0xbfb8aa3b, v89
	v_exp_f32_e32 v95, v95
	v_exp_f32_e32 v103, v97
	v_cvt_pk_bf16_f32 v97, v90, v91
	ds_write2_b64 v121, v[98:99], v[96:97] offset0:132 offset1:198
	v_add_f32_e32 v90, 1.0, v95
	v_add_f32_e32 v91, 1.0, v103
	v_rcp_f32_e32 v90, v90
	v_rcp_f32_e32 v91, v91
	v_pk_mul_f32 v[86:87], v[86:87], v[102:103] op_sel_hi:[1,0]
	v_readlane_b32 s51, v253, 10
	v_pk_fma_f32 v[86:87], v[2:3], v[86:87], v[6:7]
	v_pk_mul_f32 v[88:89], v[88:89], v[90:91]
	v_mov_b32_e32 v90, v100
	v_mov_b32_e32 v91, v92
	v_mov_b32_e32 v92, v101
	v_pk_add_f32 v[90:91], v[90:91], v[92:93]
	ds_bpermute_b32 v93, v125, v91
	ds_bpermute_b32 v92, v125, v90
	v_cvt_pk_bf16_f32 v88, v88, v89
	v_mul_f32_e32 v89, 0x4b800000, v94
	v_mul_f32_e32 v95, 0xbfb8aa3b, v86
	v_cndmask_b32_e32 v89, v94, v89, vcc
	s_waitcnt lgkmcnt(0)
	v_pk_add_f32 v[90:91], v[90:91], v[92:93]
	ds_bpermute_b32 v93, v126, v91
	ds_bpermute_b32 v92, v126, v90
	v_exp_f32_e32 v95, v95
	v_mul_f32_e32 v102, 0xbfb8aa3b, v87
	v_rsq_f32_e32 v89, v89
	v_exp_f32_e32 v103, v102
	s_waitcnt lgkmcnt(0)
	v_pk_add_f32 v[90:91], v[90:91], v[92:93]
	v_add_f32_e32 v95, 1.0, v95
	v_mul_f32_e32 v94, 0x45800000, v89
	ds_bpermute_b32 v93, v127, v91
	ds_bpermute_b32 v92, v127, v90
	v_rcp_f32_e32 v102, v95
	v_add_f32_e32 v95, 1.0, v103
	v_cndmask_b32_e32 v94, v89, v94, vcc
	v_pk_mul_f32 v[80:81], v[80:81], v[94:95] op_sel_hi:[1,0]
	v_rcp_f32_e32 v103, v95
	v_pk_fma_f32 v[80:81], v[0:1], v[80:81], v[4:5]
	s_waitcnt lgkmcnt(0)
	v_pk_add_f32 v[90:91], v[90:91], v[92:93]
	v_mul_f32_e32 v89, 0xbfb8aa3b, v80
	v_exp_f32_e32 v89, v89
	v_mul_f32_e32 v95, 0xbfb8aa3b, v81
	v_exp_f32_e32 v95, v95
	ds_bpermute_b32 v93, v128, v91
	ds_bpermute_b32 v92, v128, v90
	v_add_f32_e32 v89, 1.0, v89
	v_pk_mul_f32 v[86:87], v[86:87], v[102:103]
	v_rcp_f32_e32 v96, v89
	v_add_f32_e32 v89, 1.0, v95
	v_rcp_f32_e32 v97, v89
	v_cvt_pk_bf16_f32 v89, v86, v87
	s_waitcnt lgkmcnt(0)
	v_pk_add_f32 v[86:87], v[90:91], v[92:93]
	ds_bpermute_b32 v91, v129, v87
	ds_bpermute_b32 v90, v129, v86
	v_pk_mul_f32 v[82:83], v[82:83], v[94:95] op_sel_hi:[1,0]
	v_pk_mul_f32 v[80:81], v[80:81], v[96:97]
	v_pk_fma_f32 v[82:83], v[2:3], v[82:83], v[6:7]
	v_cvt_pk_bf16_f32 v80, v80, v81
	s_waitcnt lgkmcnt(0)
	v_pk_add_f32 v[86:87], v[86:87], v[90:91]
	ds_bpermute_b32 v91, v130, v87
	ds_bpermute_b32 v90, v130, v86
	v_mul_f32_e32 v92, 0xbfb8aa3b, v82
	v_mul_f32_e32 v93, 0xbfb8aa3b, v83
	v_exp_f32_e32 v92, v92
	v_exp_f32_e32 v93, v93
	s_waitcnt lgkmcnt(0)
	v_pk_add_f32 v[86:87], v[86:87], v[90:91]
	v_add_u32_e32 v90, 0x8800, v142
	v_pk_fma_f32 v[84:85], v[86:87], s[28:29], v[84:85] op_sel_hi:[1,0,0]
	v_add_f32_e32 v92, 1.0, v92
	v_add_f32_e32 v93, 1.0, v93
	v_mul_f32_e32 v86, 0x4b800000, v85
	v_cmp_gt_f32_e32 vcc, s1, v85
	v_rcp_f32_e32 v92, v92
	v_rcp_f32_e32 v93, v93
	v_cndmask_b32_e32 v85, v85, v86, vcc
	v_rsq_f32_e32 v85, v85
	v_readlane_b32 s54, v253, 13
	v_pk_mul_f32 v[82:83], v[82:83], v[92:93]
	v_readlane_b32 s55, v253, 14
	v_cvt_pk_bf16_f32 v81, v82, v83
	v_mul_f32_e32 v82, 0x45800000, v85
	v_cndmask_b32_e32 v82, v85, v82, vcc
	v_pk_mul_f32 v[76:77], v[76:77], v[82:83] op_sel_hi:[1,0]
	ds_write2_b64 v90, v[88:89], v[80:81] offset0:8 offset1:74
	v_pk_fma_f32 v[76:77], v[0:1], v[76:77], v[4:5]
	v_cmp_gt_f32_e32 vcc, s1, v84
	v_mul_f32_e32 v83, 0xbfb8aa3b, v76
	v_exp_f32_e32 v83, v83
	v_mul_f32_e32 v85, 0xbfb8aa3b, v77
	v_exp_f32_e32 v85, v85
	v_readlane_b32 s56, v253, 15
	v_add_f32_e32 v83, 1.0, v83
	v_rcp_f32_e32 v86, v83
	v_add_f32_e32 v83, 1.0, v85
	v_pk_mul_f32 v[78:79], v[78:79], v[82:83] op_sel_hi:[1,0]
	v_rcp_f32_e32 v87, v83
	v_pk_fma_f32 v[78:79], v[2:3], v[78:79], v[6:7]
	v_readlane_b32 s57, v253, 16
	v_mul_f32_e32 v82, 0xbfb8aa3b, v78
	v_exp_f32_e32 v82, v82
	v_mul_f32_e32 v80, 0xbfb8aa3b, v79
	v_exp_f32_e32 v81, v80
	v_mul_f32_e32 v80, 0x4b800000, v84
	v_pk_mul_f32 v[76:77], v[76:77], v[86:87]
	v_cndmask_b32_e32 v80, v84, v80, vcc
	v_cvt_pk_bf16_f32 v76, v76, v77
	v_add_f32_e32 v77, 1.0, v82
	v_rsq_f32_e32 v82, v80
	v_rcp_f32_e32 v80, v77
	v_add_f32_e32 v77, 1.0, v81
	v_rcp_f32_e32 v81, v77
	v_mul_f32_e32 v77, 0x45800000, v82
	v_cndmask_b32_e32 v82, v82, v77, vcc
	v_pk_mul_f32 v[72:73], v[72:73], v[82:83] op_sel_hi:[1,0]
	v_pk_mul_f32 v[74:75], v[74:75], v[82:83] op_sel_hi:[1,0]
	v_pk_fma_f32 v[0:1], v[0:1], v[72:73], v[4:5]
	v_pk_fma_f32 v[2:3], v[2:3], v[74:75], v[6:7]
	v_mul_f32_e32 v4, 0xbfb8aa3b, v0
	v_exp_f32_e32 v72, v4
	v_mul_f32_e32 v4, 0xbfb8aa3b, v1
	v_mul_f32_e32 v6, 0xbfb8aa3b, v2
	v_mul_f32_e32 v7, 0xbfb8aa3b, v3
	v_exp_f32_e32 v73, v4
	v_exp_f32_e32 v6, v6
	v_exp_f32_e32 v7, v7
	v_add_f32_e32 v72, 1.0, v72
	v_add_f32_e32 v73, 1.0, v73
	v_add_f32_e32 v6, 1.0, v6
	v_add_f32_e32 v7, 1.0, v7
	v_rcp_f32_e32 v72, v72
	v_rcp_f32_e32 v73, v73
	v_rcp_f32_e32 v6, v6
	v_rcp_f32_e32 v7, v7
	v_pk_mul_f32 v[4:5], v[78:79], v[80:81]
	v_pk_mul_f32 v[0:1], v[0:1], v[72:73]
	v_cvt_pk_bf16_f32 v77, v4, v5
	v_pk_mul_f32 v[2:3], v[2:3], v[6:7]
	v_cvt_pk_bf16_f32 v0, v0, v1
	v_cvt_pk_bf16_f32 v1, v2, v3
	ds_write2_b64 v90, v[76:77], v[0:1] offset0:140 offset1:206
	v_and_b32_e32 v0, 48, v122
	v_mul_u32_u24_e32 v1, 0x210, v105
	s_waitcnt lgkmcnt(0)
	s_barrier
	v_add3_u32 v92, s69, v0, v1
	ds_read_b128 v[0:3], v92 offset:32768
	ds_read_b128 v[4:7], v92 offset:32832
	ds_read_b128 v[84:87], v92 offset:41216
	ds_read_b128 v[88:91], v92 offset:41280
	s_waitcnt vmcnt(15) lgkmcnt(3)
	v_mfma_f32_16x16x32_bf16 v[72:75], v[0:3], v[56:59], 0
	v_readlane_b32 s58, v253, 17
	v_readlane_b32 s59, v253, 18
	s_waitcnt vmcnt(13)
	v_mfma_f32_16x16x32_bf16 v[76:79], v[0:3], v[60:63], 0
	s_waitcnt vmcnt(11)
	v_mfma_f32_16x16x32_bf16 v[80:83], v[0:3], v[64:67], 0
	s_waitcnt vmcnt(9)
	v_mfma_f32_16x16x32_bf16 v[0:3], v[0:3], v[68:71], 0
	s_waitcnt lgkmcnt(1)
	v_mfma_f32_16x16x32_bf16 v[56:59], v[84:87], v[56:59], 0
	v_mfma_f32_16x16x32_bf16 v[60:63], v[84:87], v[60:63], 0
	v_mfma_f32_16x16x32_bf16 v[64:67], v[84:87], v[64:67], 0
	v_mfma_f32_16x16x32_bf16 v[68:71], v[84:87], v[68:71], 0
	v_mfma_f32_16x16x32_bf16 v[72:75], v[4:7], v[40:43], v[72:75]
	v_mfma_f32_16x16x32_bf16 v[76:79], v[4:7], v[44:47], v[76:79]
	v_mfma_f32_16x16x32_bf16 v[80:83], v[4:7], v[48:51], v[80:83]
	s_waitcnt vmcnt(8)
	v_mfma_f32_16x16x32_bf16 v[0:3], v[4:7], v[52:55], v[0:3]
	s_waitcnt lgkmcnt(0)
	v_mfma_f32_16x16x32_bf16 v[4:7], v[88:91], v[40:43], v[56:59]
	v_mfma_f32_16x16x32_bf16 v[40:43], v[88:91], v[44:47], v[60:63]
	v_mfma_f32_16x16x32_bf16 v[44:47], v[88:91], v[48:51], v[64:67]
	v_mfma_f32_16x16x32_bf16 v[48:51], v[88:91], v[52:55], v[68:71]
	ds_read_b128 v[52:55], v92 offset:32896
	ds_read_b128 v[56:59], v92 offset:32960
	s_waitcnt vmcnt(7) lgkmcnt(1)
	v_mfma_f32_16x16x32_bf16 v[60:63], v[52:55], v[24:27], v[72:75]
	s_waitcnt vmcnt(5)
	v_mfma_f32_16x16x32_bf16 v[64:67], v[52:55], v[28:31], v[76:79]
	s_waitcnt vmcnt(3)
	v_mfma_f32_16x16x32_bf16 v[68:71], v[52:55], v[32:35], v[80:83]
	s_waitcnt vmcnt(1)
	v_mfma_f32_16x16x32_bf16 v[0:3], v[52:55], v[36:39], v[0:3]
	ds_read_b128 v[52:55], v92 offset:41344
	ds_read_b128 v[72:75], v92 offset:41408
	s_waitcnt lgkmcnt(1)
	v_mfma_f32_16x16x32_bf16 v[4:7], v[52:55], v[24:27], v[4:7]
	v_mfma_f32_16x16x32_bf16 v[24:27], v[52:55], v[28:31], v[40:43]
	v_mfma_f32_16x16x32_bf16 v[28:31], v[52:55], v[32:35], v[44:47]
	s_nop 2
	v_lshl_add_u64 v[44:45], s[86:87], 0, v[106:107]
	v_mfma_f32_16x16x32_bf16 v[32:35], v[52:55], v[36:39], v[48:51]
	v_lshl_add_u64 v[76:77], v[44:45], 0, v[200:201]
	v_lshl_add_u64 v[52:53], s[86:87], 0, v[110:111]
	v_lshl_add_u64 v[78:79], v[52:53], 0, v[200:201]
	v_mfma_f32_16x16x32_bf16 v[36:39], v[56:59], v[20:23], v[60:63]
	global_load_dwordx4 v[48:51], v[76:77], off offset:256
	global_load_dwordx4 v[52:55], v[78:79], off offset:256
	s_nop 0
	global_load_dwordx4 v[60:63], v[78:79], off offset:320
	v_mfma_f32_16x16x32_bf16 v[40:43], v[56:59], v[12:15], v[64:67]
	v_mfma_f32_16x16x32_bf16 v[44:47], v[56:59], v[16:19], v[68:71]
	s_waitcnt vmcnt(3)
	v_mfma_f32_16x16x32_bf16 v[0:3], v[56:59], v[8:11], v[0:3]
	v_lshl_add_u64 v[56:57], s[86:87], 0, v[112:113]
	v_lshl_add_u64 v[80:81], v[56:57], 0, v[200:201]
	v_lshl_add_u64 v[56:57], s[86:87], 0, v[108:109]
	v_lshl_add_u64 v[82:83], v[56:57], 0, v[200:201]
	s_waitcnt lgkmcnt(0)
	v_mfma_f32_16x16x32_bf16 v[4:7], v[72:75], v[20:23], v[4:7]
	global_load_dwordx4 v[20:23], v[80:81], off offset:256
	global_load_dwordx4 v[64:67], v[80:81], off offset:320
	global_load_dwordx4 v[68:71], v[82:83], off offset:320
	v_mfma_f32_16x16x32_bf16 v[12:15], v[72:75], v[12:15], v[24:27]
	ds_read_b128 v[56:59], v92 offset:33088
	v_lshlrev_b32_e32 v200, 1, v105
	s_nop 0
	global_load_dwordx4 v[24:27], v[82:83], off offset:256
	v_mfma_f32_16x16x32_bf16 v[8:11], v[72:75], v[8:11], v[32:35]
	s_nop 2
	global_load_dwordx4 v[32:35], v[76:77], off offset:320
	v_mfma_f32_16x16x32_bf16 v[16:19], v[72:75], v[16:19], v[28:31]
	s_nop 2
	ds_read_b128 v[28:31], v92 offset:33024
	s_waitcnt vmcnt(7) lgkmcnt(0)
	v_mfma_f32_16x16x32_bf16 v[36:39], v[28:31], v[48:51], v[36:39]
	s_waitcnt vmcnt(6)
	v_mfma_f32_16x16x32_bf16 v[40:43], v[28:31], v[52:55], v[40:43]
	s_waitcnt vmcnt(4)
	v_mfma_f32_16x16x32_bf16 v[44:47], v[28:31], v[20:23], v[44:47]
	s_waitcnt vmcnt(1)
	v_mfma_f32_16x16x32_bf16 v[0:3], v[28:31], v[24:27], v[0:3]
	ds_read_b128 v[28:31], v92 offset:41472
	ds_read_b128 v[72:75], v92 offset:41536
	s_waitcnt lgkmcnt(1)
	v_mfma_f32_16x16x32_bf16 v[4:7], v[28:31], v[48:51], v[4:7]
	ds_read_b128 v[48:51], v92 offset:33152
	v_mfma_f32_16x16x32_bf16 v[12:15], v[28:31], v[52:55], v[12:15]
	global_load_dwordx4 v[52:55], v[76:77], off offset:448
	v_mfma_f32_16x16x32_bf16 v[16:19], v[28:31], v[20:23], v[16:19]
	v_mfma_f32_16x16x32_bf16 v[8:11], v[28:31], v[24:27], v[8:11]
	s_waitcnt vmcnt(1)
	v_mfma_f32_16x16x32_bf16 v[20:23], v[56:59], v[32:35], v[36:39]
	v_mfma_f32_16x16x32_bf16 v[24:27], v[56:59], v[60:63], v[40:43]
	s_nop 1
	global_load_dwordx4 v[36:39], v[76:77], off offset:384
	v_mfma_f32_16x16x32_bf16 v[28:31], v[56:59], v[64:67], v[44:47]
	global_load_dwordx4 v[40:43], v[78:79], off offset:384
	s_waitcnt lgkmcnt(1)
	v_mfma_f32_16x16x32_bf16 v[4:7], v[72:75], v[32:35], v[4:7]
	global_load_dwordx4 v[32:35], v[80:81], off offset:384
	global_load_dwordx4 v[44:47], v[82:83], off offset:384
	v_mfma_f32_16x16x32_bf16 v[12:15], v[72:75], v[60:63], v[12:15]
	global_load_dwordx4 v[60:63], v[78:79], off offset:448
	v_mfma_f32_16x16x32_bf16 v[0:3], v[56:59], v[68:71], v[0:3]
	ds_read_b128 v[56:59], v92 offset:33216
	v_mfma_f32_16x16x32_bf16 v[16:19], v[72:75], v[64:67], v[16:19]
	global_load_dwordx4 v[64:67], v[80:81], off offset:448
	v_mfma_f32_16x16x32_bf16 v[8:11], v[72:75], v[68:71], v[8:11]
	global_load_dwordx4 v[68:71], v[82:83], off offset:448
	s_waitcnt vmcnt(6) lgkmcnt(1)
	v_mfma_f32_16x16x32_bf16 v[20:23], v[48:51], v[36:39], v[20:23]
	s_waitcnt vmcnt(5)
	v_mfma_f32_16x16x32_bf16 v[24:27], v[48:51], v[40:43], v[24:27]
	s_waitcnt vmcnt(4)
	v_mfma_f32_16x16x32_bf16 v[28:31], v[48:51], v[32:35], v[28:31]
	s_waitcnt vmcnt(3)
	v_mfma_f32_16x16x32_bf16 v[0:3], v[48:51], v[44:47], v[0:3]
	ds_read_b128 v[48:51], v92 offset:41600
	ds_read_b128 v[72:75], v92 offset:41664
	s_waitcnt lgkmcnt(1)
	v_mfma_f32_16x16x32_bf16 v[16:19], v[48:51], v[32:35], v[16:19]
	v_lshrrev_b32_e32 v32, 2, v123
	v_and_b32_e32 v34, 0xffffffc0, v122
	v_and_or_b32 v32, v32, 12, s2
	v_mfma_f32_16x16x32_bf16 v[20:23], v[56:59], v[52:55], v[20:23]
	v_ashrrev_i32_e32 v35, 31, v34
	v_lshl_add_u64 v[34:35], v[34:35], 1, s[22:23]
	v_ashrrev_i32_e32 v33, 31, v32
	s_waitcnt vmcnt(2)
	v_mfma_f32_16x16x32_bf16 v[24:27], v[56:59], v[60:63], v[24:27]
	v_lshl_add_u64 v[34:35], v[34:35], 0, v[200:201]
	s_nop 1
	v_cvt_pk_bf16_f32 v20, v20, s0
	s_bfe_u32 s2, s94, 0x20001
	s_waitcnt vmcnt(1)
	v_mfma_f32_16x16x32_bf16 v[28:31], v[56:59], v[64:67], v[28:31]
	s_cmp_gt_i32 s40, 31
	s_waitcnt vmcnt(0)
	v_mfma_f32_16x16x32_bf16 v[0:3], v[56:59], v[68:71], v[0:3]
	v_mfma_f32_16x16x32_bf16 v[4:7], v[48:51], v[36:39], v[4:7]
	v_lshlrev_b64 v[36:37], 11, v[32:33]
	v_lshl_add_u64 v[36:37], v[34:35], 0, v[36:37]
	global_store_short v[36:37], v20, off
	v_cvt_pk_bf16_f32 v20, v24, s0
	global_store_short v[36:37], v20, off offset:32
	v_cvt_pk_bf16_f32 v20, v28, s0
	s_nop 0
	v_cvt_pk_bf16_f32 v0, v0, s0
	global_store_short v[36:37], v20, off offset:64
	global_store_short v[36:37], v0, off offset:96
	v_or_b32_e32 v36, 1, v32
	v_ashrrev_i32_e32 v37, 31, v36
	v_lshlrev_b64 v[36:37], 11, v[36:37]
	v_lshl_add_u64 v[36:37], v[34:35], 0, v[36:37]
	v_cvt_pk_bf16_f32 v0, v21, s0
	global_store_short v[36:37], v0, off
	v_cvt_pk_bf16_f32 v0, v25, s0
	global_store_short v[36:37], v0, off offset:32
	v_cvt_pk_bf16_f32 v0, v29, s0
	global_store_short v[36:37], v0, off offset:64
	v_cvt_pk_bf16_f32 v0, v1, s0
	global_store_short v[36:37], v0, off offset:96
	v_or_b32_e32 v0, 2, v32
	v_ashrrev_i32_e32 v1, 31, v0
	v_lshlrev_b64 v[0:1], 11, v[0:1]
	v_lshl_add_u64 v[0:1], v[34:35], 0, v[0:1]
	v_cvt_pk_bf16_f32 v20, v22, s0
	global_store_short v[0:1], v20, off
	v_cvt_pk_bf16_f32 v20, v26, s0
	global_store_short v[0:1], v20, off offset:32
	v_cvt_pk_bf16_f32 v20, v30, s0
	v_cvt_pk_bf16_f32 v2, v2, s0
	global_store_short v[0:1], v20, off offset:64
	global_store_short v[0:1], v2, off offset:96
	v_or_b32_e32 v0, 3, v32
	v_ashrrev_i32_e32 v1, 31, v0
	v_lshlrev_b64 v[0:1], 11, v[0:1]
	v_mfma_f32_16x16x32_bf16 v[12:15], v[48:51], v[40:43], v[12:15]
	v_lshl_add_u64 v[0:1], v[34:35], 0, v[0:1]
	v_cvt_pk_bf16_f32 v2, v23, s0
	global_store_short v[0:1], v2, off
	v_cvt_pk_bf16_f32 v2, v27, s0
	v_mfma_f32_16x16x32_bf16 v[8:11], v[48:51], v[44:47], v[8:11]
	global_store_short v[0:1], v2, off offset:32
	v_cvt_pk_bf16_f32 v2, v31, s0
	global_store_short v[0:1], v2, off offset:64
	s_waitcnt lgkmcnt(0)
	v_mfma_f32_16x16x32_bf16 v[4:7], v[72:75], v[52:55], v[4:7]
	v_cvt_pk_bf16_f32 v2, v3, s0
	global_store_short v[0:1], v2, off offset:96
	v_or_b32_e32 v0, 16, v32
	v_mfma_f32_16x16x32_bf16 v[12:15], v[72:75], v[60:63], v[12:15]
	v_ashrrev_i32_e32 v1, 31, v0
	v_lshlrev_b64 v[0:1], 11, v[0:1]
	v_lshl_add_u64 v[0:1], v[34:35], 0, v[0:1]
	v_mfma_f32_16x16x32_bf16 v[16:19], v[72:75], v[64:67], v[16:19]
	v_cvt_pk_bf16_f32 v2, v4, s0
	global_store_short v[0:1], v2, off
	s_nop 1
	v_cvt_pk_bf16_f32 v2, v12, s0
	v_mfma_f32_16x16x32_bf16 v[8:11], v[72:75], v[68:71], v[8:11]
	global_store_short v[0:1], v2, off offset:32
	s_nop 0
	v_cvt_pk_bf16_f32 v2, v16, s0
	global_store_short v[0:1], v2, off offset:64
	v_mov_b32_e32 v38, v229
	v_mov_b32_e32 v22, v229
	s_nop 1
	v_cvt_pk_bf16_f32 v2, v8, s0
	global_store_short v[0:1], v2, off offset:96
	v_or_b32_e32 v0, 17, v32
	v_ashrrev_i32_e32 v1, 31, v0
	v_lshlrev_b64 v[0:1], 11, v[0:1]
	v_lshl_add_u64 v[0:1], v[34:35], 0, v[0:1]
	v_cvt_pk_bf16_f32 v2, v5, s0
	global_store_short v[0:1], v2, off
	v_cvt_pk_bf16_f32 v2, v13, s0
	global_store_short v[0:1], v2, off offset:32
	v_cvt_pk_bf16_f32 v2, v17, s0
	global_store_short v[0:1], v2, off offset:64
	v_cvt_pk_bf16_f32 v2, v9, s0
	global_store_short v[0:1], v2, off offset:96
	v_or_b32_e32 v0, 18, v32
	v_ashrrev_i32_e32 v1, 31, v0
	v_lshlrev_b64 v[0:1], 11, v[0:1]
	v_lshl_add_u64 v[0:1], v[34:35], 0, v[0:1]
	v_cvt_pk_bf16_f32 v2, v6, s0
	global_store_short v[0:1], v2, off
	v_cvt_pk_bf16_f32 v2, v14, s0
	global_store_short v[0:1], v2, off offset:32
	v_cvt_pk_bf16_f32 v2, v18, s0
	global_store_short v[0:1], v2, off offset:64
	v_cvt_pk_bf16_f32 v2, v10, s0
	global_store_short v[0:1], v2, off offset:96
	v_or_b32_e32 v0, 19, v32
	v_ashrrev_i32_e32 v1, 31, v0
	v_lshlrev_b64 v[0:1], 11, v[0:1]
	v_lshl_add_u64 v[0:1], v[34:35], 0, v[0:1]
	v_cvt_pk_bf16_f32 v2, v7, s0
	global_store_short v[0:1], v2, off
	v_cvt_pk_bf16_f32 v2, v15, s0
	global_store_short v[0:1], v2, off offset:32
	v_cvt_pk_bf16_f32 v2, v19, s0
	global_store_short v[0:1], v2, off offset:64
	v_cvt_pk_bf16_f32 v2, v11, s0
	s_cselect_b64 s[0:1], -1, 0
	s_or_b32 s28, s2, s79
	s_ashr_i32 s29, s28, 31
	s_lshl_b64 s[28:29], s[28:29], 2
	s_add_u32 s28, s52, s28
	s_addc_u32 s29, s53, s29
	global_store_short v[0:1], v2, off offset:96
	s_add_u32 s38, s20, s38
	s_waitcnt lgkmcnt(0)
	s_barrier
	s_addc_u32 s39, s21, s39
	s_lshl_b32 s41, s2, 7
	global_load_dword v41, v201, s[28:29]
	s_add_u32 s38, s38, s41
	v_lshlrev_b32_e32 v0, 2, v22
	v_and_b32_e32 v23, 60, v0
	s_addc_u32 s39, s39, 0
	v_lshlrev_b32_e32 v200, 1, v23
	v_lshl_add_u64 v[0:1], s[38:39], 0, v[200:201]
	s_mov_b64 s[28:29], 0x1200
	v_lshl_add_u64 v[0:1], v[0:1], 0, s[28:29]
	v_ashrrev_i32_e32 v2, 4, v22
	v_mad_i64_i32 v[2:3], s[28:29], v2, s92, v[0:1]
	global_load_dwordx2 v[2:3], v[2:3], off
	v_add_u32_e32 v24, 0x100, v22
	v_ashrrev_i32_e32 v4, 4, v24
	v_mad_i64_i32 v[4:5], s[28:29], v4, s92, v[0:1]
	global_load_dwordx2 v[4:5], v[4:5], off
	v_add_u32_e32 v25, 0x200, v22
	v_ashrrev_i32_e32 v6, 4, v25
	v_mad_i64_i32 v[6:7], s[28:29], v6, s92, v[0:1]
	global_load_dwordx2 v[6:7], v[6:7], off
	v_add_u32_e32 v26, 0x300, v22
	v_ashrrev_i32_e32 v8, 4, v26
	v_mad_i64_i32 v[8:9], s[28:29], v8, s92, v[0:1]
	global_load_dwordx2 v[8:9], v[8:9], off
	v_add_u32_e32 v27, 0x400, v22
	v_ashrrev_i32_e32 v10, 4, v27
	v_mad_i64_i32 v[10:11], s[28:29], v10, s92, v[0:1]
	global_load_dwordx2 v[10:11], v[10:11], off
	v_add_u32_e32 v28, 0x500, v22
	s_lshl_b32 s38, s80, 1
	v_ashrrev_i32_e32 v12, 4, v28
	s_or_b32 s28, s41, s38
	v_mad_i64_i32 v[12:13], s[38:39], v12, s92, v[0:1]
	s_add_u32 s28, s20, s28
	global_load_dwordx2 v[12:13], v[12:13], off
	v_add_u32_e32 v29, 0x600, v22
	v_add_u32_e32 v30, 0x700, v22
	v_bfe_u32 v31, v38, 2, 1
	s_addc_u32 s29, s21, 0
	v_ashrrev_i32_e32 v14, 4, v29
	v_ashrrev_i32_e32 v16, 4, v30
	v_lshlrev_b32_e32 v200, 6, v31
	v_lshlrev_b32_e32 v39, 3, v38
	v_mad_i64_i32 v[14:15], s[38:39], v14, s92, v[0:1]
	v_mad_i64_i32 v[0:1], s[38:39], v16, s92, v[0:1]
	v_lshl_add_u64 v[16:17], s[28:29], 0, v[200:201]
	v_and_b32_e32 v200, 24, v39
	v_ashrrev_i32_e32 v40, 3, v38
	global_load_dwordx2 v[14:15], v[14:15], off
	v_lshl_add_u64 v[16:17], v[16:17], 0, v[200:201]
	v_add_u32_e32 v18, s3, v40
	v_mad_i64_i32 v[18:19], s[28:29], v18, s92, v[16:17]
	global_load_dwordx2 v[0:1], v[0:1], off
	s_nop 0
	global_load_dwordx2 v[20:21], v[18:19], off
	s_nop 0
	global_load_dwordx2 v[18:19], v[18:19], off offset:32
	v_mov_b32_e32 v32, s69
	s_movk_i32 s38, 0x110
	v_ashrrev_i32_e32 v22, 3, v22
	v_mad_u32_u24 v23, v23, s38, v32
	v_and_b32_e32 v22, -2, v22
	v_add_u32_e32 v22, v23, v22
	v_add_u32_e32 v54, 0x100, v38
	v_ashrrev_i32_e32 v42, 3, v54
	v_add_u32_e32 v46, s3, v42
	v_mad_i64_i32 v[48:49], vcc, v46, s92, v[16:17]
	global_load_dwordx2 v[60:61], v[48:49], off
	global_load_dwordx2 v[62:63], v[48:49], off offset:32
	v_add_u32_e32 v55, 0x200, v38
	v_ashrrev_i32_e32 v43, 3, v55
	v_add_u32_e32 v46, s3, v43
	v_mad_i64_i32 v[48:49], vcc, v46, s92, v[16:17]
	global_load_dwordx2 v[64:65], v[48:49], off
	global_load_dwordx2 v[66:67], v[48:49], off offset:32
	v_add_u32_e32 v56, 0x300, v38
	v_ashrrev_i32_e32 v44, 3, v56
	v_add_u32_e32 v46, s3, v44
	v_mad_i64_i32 v[48:49], vcc, v46, s92, v[16:17]
	global_load_dwordx2 v[68:69], v[48:49], off
	global_load_dwordx2 v[70:71], v[48:49], off offset:32
	s_waitcnt vmcnt(15)
	ds_write_b16 v22, v2 offset:17408
	ds_write_b16_d16_hi v22, v2 offset:17680
	ds_write_b16 v22, v3 offset:17952
	ds_write_b16_d16_hi v22, v3 offset:18224
	v_ashrrev_i32_e32 v2, 3, v24
	v_and_b32_e32 v2, -2, v2
	v_add_u32_e32 v2, v23, v2
	s_waitcnt vmcnt(14)
	ds_write_b16 v2, v4 offset:17408
	ds_write_b16_d16_hi v2, v4 offset:17680
	ds_write_b16 v2, v5 offset:17952
	ds_write_b16_d16_hi v2, v5 offset:18224
	v_ashrrev_i32_e32 v2, 3, v25
	v_and_b32_e32 v2, -2, v2
	v_add_u32_e32 v2, v23, v2
	s_waitcnt vmcnt(13)
	ds_write_b16 v2, v6 offset:17408
	ds_write_b16_d16_hi v2, v6 offset:17680
	ds_write_b16 v2, v7 offset:17952
	ds_write_b16_d16_hi v2, v7 offset:18224
	v_ashrrev_i32_e32 v2, 3, v26
	v_and_b32_e32 v2, -2, v2
	v_add_u32_e32 v2, v23, v2
	s_waitcnt vmcnt(12)
	ds_write_b16 v2, v8 offset:17408
	ds_write_b16_d16_hi v2, v8 offset:17680
	ds_write_b16 v2, v9 offset:17952
	ds_write_b16_d16_hi v2, v9 offset:18224
	v_ashrrev_i32_e32 v2, 3, v27
	v_and_b32_e32 v2, -2, v2
	v_add_u32_e32 v2, v23, v2
	s_waitcnt vmcnt(11)
	ds_write_b16 v2, v10 offset:17408
	ds_write_b16_d16_hi v2, v10 offset:17680
	ds_write_b16 v2, v11 offset:17952
	ds_write_b16_d16_hi v2, v11 offset:18224
	v_ashrrev_i32_e32 v2, 3, v28
	v_and_b32_e32 v2, -2, v2
	v_add_u32_e32 v2, v23, v2
	s_waitcnt vmcnt(10)
	ds_write_b16 v2, v12 offset:17408
	ds_write_b16_d16_hi v2, v12 offset:17680
	ds_write_b16 v2, v13 offset:17952
	ds_write_b16_d16_hi v2, v13 offset:18224
	v_ashrrev_i32_e32 v2, 3, v29
	s_cmp_lt_i32 s40, 32
	v_and_b32_e32 v2, -2, v2
	s_cselect_b64 s[28:29], -1, 0
	v_add_u32_e32 v2, v23, v2
	s_waitcnt vmcnt(9)
	ds_write_b16 v2, v14 offset:17408
	ds_write_b16_d16_hi v2, v14 offset:17680
	ds_write_b16 v2, v15 offset:17952
	ds_write_b16_d16_hi v2, v15 offset:18224
	v_ashrrev_i32_e32 v2, 3, v30
	s_and_b64 vcc, s[28:29], exec
	s_mov_b32 s28, 0x80000380
	v_and_b32_e32 v2, -2, v2
	s_cselect_b32 s28, 0x80, s28
	v_add_u32_e32 v2, v23, v2
	v_cmp_eq_u32_e64 s[38:39], 0, v31
	s_and_b32 s28, s28, s3
	s_waitcnt vmcnt(7)
	v_lshlrev_b32_e32 v12, 16, v20
	v_and_b32_e32 v13, 0xffff0000, v20
	v_lshlrev_b32_e32 v15, 16, v21
	s_waitcnt vmcnt(6)
	v_lshlrev_b32_e32 v8, 16, v18
	v_and_b32_e32 v9, 0xffff0000, v18
	v_lshlrev_b32_e32 v14, 16, v19
	v_and_b32_e32 v11, 0xffff0000, v19
	v_and_b32_e32 v10, 0xffff0000, v21
	s_mov_b64 s[40:41], -1
	ds_write_b16 v2, v0 offset:17408
	ds_write_b16_d16_hi v2, v0 offset:17680
	ds_write_b16 v2, v1 offset:17952
	ds_write_b16_d16_hi v2, v1 offset:18224
	s_and_b64 vcc, exec, s[0:1]
	s_cbranch_vccz .Lkv_norot_b
	v_add_u32_e32 v32, s28, v40
	v_ashrrev_i32_e32 v32, 6, v32
	v_bfe_u32 v33, v38, 3, 6
	v_cndmask_b32_e64 v32, v33, v32, s[38:39]
	v_lshl_or_b32 v32, v32, 5, v200
	v_lshlrev_b32_e32 v50, 2, v32
	global_load_dwordx4 v[72:75], v50, s[12:13]
	global_load_dwordx4 v[76:79], v50, s[12:13] offset:16
	v_add_u32_e32 v32, s28, v42
	v_ashrrev_i32_e32 v32, 6, v32
	v_bfe_u32 v33, v54, 3, 6
	v_cndmask_b32_e64 v32, v33, v32, s[38:39]
	v_lshl_or_b32 v32, v32, 5, v200
	v_lshlrev_b32_e32 v51, 2, v32
	global_load_dwordx4 v[80:83], v51, s[12:13]
	global_load_dwordx4 v[84:87], v51, s[12:13] offset:16
	v_add_u32_e32 v32, s28, v43
	v_ashrrev_i32_e32 v32, 6, v32
	v_bfe_u32 v33, v55, 3, 6
	v_cndmask_b32_e64 v32, v33, v32, s[38:39]
	v_lshl_or_b32 v32, v32, 5, v200
	v_lshlrev_b32_e32 v52, 2, v32
	global_load_dwordx4 v[88:91], v52, s[12:13]
	global_load_dwordx4 v[92:95], v52, s[12:13] offset:16
	v_add_u32_e32 v32, s28, v44
	v_ashrrev_i32_e32 v32, 6, v32
	v_bfe_u32 v33, v56, 3, 6
	v_cndmask_b32_e64 v32, v33, v32, s[38:39]
	v_lshl_or_b32 v32, v32, 5, v200
	v_lshlrev_b32_e32 v53, 2, v32
	global_load_dwordx4 v[96:99], v53, s[12:13]
	global_load_dwordx4 v[100:103], v53, s[12:13] offset:16
	s_waitcnt vmcnt(0)
	v_mul_f32_e32 v34, v8, v73
	v_mul_f32_e32 v35, v12, v73
	v_fma_f32 v0, v12, v72, -v34
	v_fma_f32 v6, v8, v72, v35
	v_mul_f32_e32 v34, v9, v75
	v_mul_f32_e32 v35, v13, v75
	v_fma_f32 v1, v13, v74, -v34
	v_fma_f32 v7, v9, v74, v35
	v_mul_f32_e32 v34, v14, v77
	v_mul_f32_e32 v35, v15, v77
	v_fma_f32 v2, v15, v76, -v34
	v_fma_f32 v4, v14, v76, v35
	v_mul_f32_e32 v34, v11, v79
	v_mul_f32_e32 v35, v10, v79
	v_fma_f32 v3, v10, v78, -v34
	v_fma_f32 v5, v11, v78, v35
	v_lshlrev_b32_e32 v32, 16, v60
	v_lshlrev_b32_e32 v33, 16, v62
	v_mul_f32_e32 v34, v33, v81
	v_mul_f32_e32 v35, v32, v81
	v_fma_f32 v8, v32, v80, -v34
	v_fma_f32 v14, v33, v80, v35
	v_and_b32_e32 v32, 0xffff0000, v60
	v_and_b32_e32 v33, 0xffff0000, v62
	v_mul_f32_e32 v34, v33, v83
	v_mul_f32_e32 v35, v32, v83
	v_fma_f32 v9, v32, v82, -v34
	v_fma_f32 v15, v33, v82, v35
	v_lshlrev_b32_e32 v32, 16, v61
	v_lshlrev_b32_e32 v33, 16, v63
	v_mul_f32_e32 v34, v33, v85
	v_mul_f32_e32 v35, v32, v85
	v_fma_f32 v10, v32, v84, -v34
	v_fma_f32 v12, v33, v84, v35
	v_and_b32_e32 v32, 0xffff0000, v61
	v_and_b32_e32 v33, 0xffff0000, v63
	v_mul_f32_e32 v34, v33, v87
	v_mul_f32_e32 v35, v32, v87
	v_fma_f32 v11, v32, v86, -v34
	v_fma_f32 v13, v33, v86, v35
	v_lshlrev_b32_e32 v32, 16, v64
	v_lshlrev_b32_e32 v33, 16, v66
	v_mul_f32_e32 v34, v33, v89
	v_mul_f32_e32 v35, v32, v89
	v_fma_f32 v18, v32, v88, -v34
	v_fma_f32 v24, v33, v88, v35
	v_and_b32_e32 v32, 0xffff0000, v64
	v_and_b32_e32 v33, 0xffff0000, v66
	v_mul_f32_e32 v34, v33, v91
	v_mul_f32_e32 v35, v32, v91
	v_fma_f32 v19, v32, v90, -v34
	v_fma_f32 v25, v33, v90, v35
	v_lshlrev_b32_e32 v32, 16, v65
	v_lshlrev_b32_e32 v33, 16, v67
	v_mul_f32_e32 v34, v33, v93
	v_mul_f32_e32 v35, v32, v93
	v_fma_f32 v20, v32, v92, -v34
	v_fma_f32 v22, v33, v92, v35
	v_and_b32_e32 v32, 0xffff0000, v65
	v_and_b32_e32 v33, 0xffff0000, v67
	v_mul_f32_e32 v34, v33, v95
	v_mul_f32_e32 v35, v32, v95
	v_fma_f32 v21, v32, v94, -v34
	v_fma_f32 v23, v33, v94, v35
	v_lshlrev_b32_e32 v32, 16, v68
	v_lshlrev_b32_e32 v33, 16, v70
	v_mul_f32_e32 v34, v33, v97
	v_mul_f32_e32 v35, v32, v97
	v_fma_f32 v16, v32, v96, -v34
	v_fma_f32 v30, v33, v96, v35
	v_and_b32_e32 v32, 0xffff0000, v68
	v_and_b32_e32 v33, 0xffff0000, v70
	v_mul_f32_e32 v34, v33, v99
	v_mul_f32_e32 v35, v32, v99
	v_fma_f32 v17, v32, v98, -v34
	v_fma_f32 v31, v33, v98, v35
	v_lshlrev_b32_e32 v32, 16, v69
	v_lshlrev_b32_e32 v33, 16, v71
	v_mul_f32_e32 v34, v33, v101
	v_mul_f32_e32 v35, v32, v101
	v_fma_f32 v26, v32, v100, -v34
	v_fma_f32 v28, v33, v100, v35
	v_and_b32_e32 v32, 0xffff0000, v69
	v_and_b32_e32 v33, 0xffff0000, v71
	v_mul_f32_e32 v34, v33, v103
	v_mul_f32_e32 v35, v32, v103
	v_fma_f32 v27, v32, v102, -v34
	v_fma_f32 v29, v33, v102, v35
	s_branch .Lkv_done_b
